# GEMM step barrier hook: next step's first A-fragment reads issued before the DMA pieces
# baseline (speedup 1.0000x reference)
.Lg2_ff2_loop17:
	s_add_u32 s58, s58, 0x800
	s_addc_u32 s59, s59, 0
	global_load_dwordx4 v[200:203], v160, s[58:59] offset:0
	global_load_dwordx4 v[204:207], v160, s[58:59] offset:1024
	global_load_dwordx4 v[208:211], v161, s[58:59] offset:0
	global_load_dwordx4 v[240:243], v161, s[58:59] offset:1024
	ds_read_b128 v[164:167], v156 offset:8192
	ds_read_b128 v[168:171], v156 offset:10240
	ds_read_b128 v[172:175], v156 offset:12288
	ds_read_b128 v[176:179], v156 offset:14336
	s_waitcnt lgkmcnt(4)
	v_mfma_f32_16x16x32_bf16 v[0:3], v[184:187], v[136:139], v[0:3]
	v_mfma_f32_16x16x32_bf16 v[4:7], v[192:195], v[136:139], v[4:7]
	v_mfma_f32_16x16x32_bf16 v[8:11], v[184:187], v[140:143], v[8:11]
	v_mfma_f32_16x16x32_bf16 v[12:15], v[192:195], v[140:143], v[12:15]
	v_mfma_f32_16x16x32_bf16 v[16:19], v[184:187], v[144:147], v[16:19]
	v_mfma_f32_16x16x32_bf16 v[20:23], v[192:195], v[144:147], v[20:23]
	v_mfma_f32_16x16x32_bf16 v[24:27], v[184:187], v[148:151], v[24:27]
	v_mfma_f32_16x16x32_bf16 v[28:31], v[192:195], v[148:151], v[28:31]
	ds_read_b128 v[136:139], v156 offset:16384
	ds_read_b128 v[140:143], v156 offset:18432
	ds_read_b128 v[144:147], v156 offset:20480
	ds_read_b128 v[148:151], v156 offset:22528
	s_waitcnt lgkmcnt(4)
	v_mfma_f32_16x16x32_bf16 v[32:35], v[184:187], v[164:167], v[32:35]
	v_mfma_f32_16x16x32_bf16 v[36:39], v[192:195], v[164:167], v[36:39]
	v_mfma_f32_16x16x32_bf16 v[40:43], v[184:187], v[168:171], v[40:43]
	v_mfma_f32_16x16x32_bf16 v[44:47], v[192:195], v[168:171], v[44:47]
	v_mfma_f32_16x16x32_bf16 v[48:51], v[184:187], v[172:175], v[48:51]
	v_mfma_f32_16x16x32_bf16 v[52:55], v[192:195], v[172:175], v[52:55]
	v_mfma_f32_16x16x32_bf16 v[56:59], v[184:187], v[176:179], v[56:59]
	v_mfma_f32_16x16x32_bf16 v[60:63], v[192:195], v[176:179], v[60:63]
	ds_read_b128 v[164:167], v156 offset:24576
	ds_read_b128 v[168:171], v156 offset:26624
	ds_read_b128 v[172:175], v156 offset:28672
	ds_read_b128 v[176:179], v156 offset:30720
	ds_read_b128 v[180:183], v156 offset:32768
	s_waitcnt lgkmcnt(5)
	v_mfma_f32_16x16x32_bf16 v[64:67], v[184:187], v[136:139], v[64:67]
	v_mfma_f32_16x16x32_bf16 v[68:71], v[192:195], v[136:139], v[68:71]
	v_mfma_f32_16x16x32_bf16 v[72:75], v[184:187], v[140:143], v[72:75]
	v_mfma_f32_16x16x32_bf16 v[76:79], v[192:195], v[140:143], v[76:79]
	v_mfma_f32_16x16x32_bf16 v[80:83], v[184:187], v[144:147], v[80:83]
	v_mfma_f32_16x16x32_bf16 v[84:87], v[192:195], v[144:147], v[84:87]
	v_mfma_f32_16x16x32_bf16 v[88:91], v[184:187], v[148:151], v[88:91]
	v_mfma_f32_16x16x32_bf16 v[92:95], v[192:195], v[148:151], v[92:95]
	ds_read_b128 v[136:139], v157 offset:0
	ds_read_b128 v[140:143], v157 offset:2048
	ds_read_b128 v[144:147], v157 offset:4096
	ds_read_b128 v[148:151], v157 offset:6144
	s_waitcnt lgkmcnt(4)
	v_mfma_f32_16x16x32_bf16 v[96:99], v[184:187], v[164:167], v[96:99]
	v_mfma_f32_16x16x32_bf16 v[100:103], v[192:195], v[164:167], v[100:103]
	v_mfma_f32_16x16x32_bf16 v[104:107], v[184:187], v[168:171], v[104:107]
	v_mfma_f32_16x16x32_bf16 v[108:111], v[192:195], v[168:171], v[108:111]
	v_mfma_f32_16x16x32_bf16 v[112:115], v[184:187], v[172:175], v[112:115]
	v_mfma_f32_16x16x32_bf16 v[116:119], v[192:195], v[172:175], v[116:119]
	v_mfma_f32_16x16x32_bf16 v[120:123], v[184:187], v[176:179], v[120:123]
	v_mfma_f32_16x16x32_bf16 v[124:127], v[192:195], v[176:179], v[124:127]
	v_mfma_f32_16x16x32_bf16 v[128:131], v[184:187], v[180:183], v[128:131]
	v_mfma_f32_16x16x32_bf16 v[132:135], v[192:195], v[180:183], v[132:135]
	ds_read_b128 v[164:167], v157 offset:8192
	ds_read_b128 v[168:171], v157 offset:10240
	ds_read_b128 v[172:175], v157 offset:12288
	ds_read_b128 v[176:179], v157 offset:14336
	s_waitcnt lgkmcnt(4)
	v_mfma_f32_16x16x32_bf16 v[0:3], v[188:191], v[136:139], v[0:3]
	v_mfma_f32_16x16x32_bf16 v[4:7], v[196:199], v[136:139], v[4:7]
	v_mfma_f32_16x16x32_bf16 v[8:11], v[188:191], v[140:143], v[8:11]
	v_mfma_f32_16x16x32_bf16 v[12:15], v[196:199], v[140:143], v[12:15]
	v_mfma_f32_16x16x32_bf16 v[16:19], v[188:191], v[144:147], v[16:19]
	v_mfma_f32_16x16x32_bf16 v[20:23], v[196:199], v[144:147], v[20:23]
	v_mfma_f32_16x16x32_bf16 v[24:27], v[188:191], v[148:151], v[24:27]
	v_mfma_f32_16x16x32_bf16 v[28:31], v[196:199], v[148:151], v[28:31]
	ds_read_b128 v[136:139], v157 offset:16384
	ds_read_b128 v[140:143], v157 offset:18432
	ds_read_b128 v[144:147], v157 offset:20480
	ds_read_b128 v[148:151], v157 offset:22528
	s_waitcnt lgkmcnt(4)
	v_mfma_f32_16x16x32_bf16 v[32:35], v[188:191], v[164:167], v[32:35]
	v_mfma_f32_16x16x32_bf16 v[36:39], v[196:199], v[164:167], v[36:39]
	v_mfma_f32_16x16x32_bf16 v[40:43], v[188:191], v[168:171], v[40:43]
	v_mfma_f32_16x16x32_bf16 v[44:47], v[196:199], v[168:171], v[44:47]
	v_mfma_f32_16x16x32_bf16 v[48:51], v[188:191], v[172:175], v[48:51]
	v_mfma_f32_16x16x32_bf16 v[52:55], v[196:199], v[172:175], v[52:55]
	v_mfma_f32_16x16x32_bf16 v[56:59], v[188:191], v[176:179], v[56:59]
	v_mfma_f32_16x16x32_bf16 v[60:63], v[196:199], v[176:179], v[60:63]
	ds_read_b128 v[164:167], v157 offset:24576
	ds_read_b128 v[168:171], v157 offset:26624
	ds_read_b128 v[172:175], v157 offset:28672
	ds_read_b128 v[176:179], v157 offset:30720
	ds_read_b128 v[180:183], v157 offset:32768
	s_waitcnt lgkmcnt(5)
	v_mfma_f32_16x16x32_bf16 v[64:67], v[188:191], v[136:139], v[64:67]
	v_mfma_f32_16x16x32_bf16 v[68:71], v[196:199], v[136:139], v[68:71]
	v_mfma_f32_16x16x32_bf16 v[72:75], v[188:191], v[140:143], v[72:75]
	v_mfma_f32_16x16x32_bf16 v[76:79], v[196:199], v[140:143], v[76:79]
	v_mfma_f32_16x16x32_bf16 v[80:83], v[188:191], v[144:147], v[80:83]
	v_mfma_f32_16x16x32_bf16 v[84:87], v[196:199], v[144:147], v[84:87]
	v_mfma_f32_16x16x32_bf16 v[88:91], v[188:191], v[148:151], v[88:91]
	v_mfma_f32_16x16x32_bf16 v[92:95], v[196:199], v[148:151], v[92:95]
	s_waitcnt vmcnt(0) lgkmcnt(0)
	s_barrier
	ds_read_b128 v[136:139], v158 offset:0
	ds_read_b128 v[140:143], v158 offset:2048
	ds_read_b128 v[144:147], v158 offset:4096
	ds_read_b128 v[148:151], v158 offset:6144
	s_cmp_ge_u32 s63, 62
	s_cbranch_scc1 .Lg2_ff2_nd17_0
	s_add_u32 s56, s56, 0x80
	s_addc_u32 s57, s57, 0
	s_add_u32 m0, s62, 0x0
	s_add_u32 s4, s56, 0x0
	s_addc_u32 s5, s57, 0
	global_load_lds_dwordx4 v162, s[4:5]
	s_add_u32 m0, s62, 0x1000
	s_add_u32 s4, s56, 0x40000
	s_addc_u32 s5, s57, 0
	global_load_lds_dwordx4 v162, s[4:5]
	s_add_u32 m0, s62, 0x2000
	s_add_u32 s4, s56, 0x80000
	s_addc_u32 s5, s57, 0
	global_load_lds_dwordx4 v162, s[4:5]
	s_add_u32 m0, s62, 0x3000
	s_add_u32 s4, s56, 0xc0000
	s_addc_u32 s5, s57, 0
	global_load_lds_dwordx4 v162, s[4:5]
	s_add_u32 m0, s62, 0x4000
	s_add_u32 s4, s56, 0x100000
	s_addc_u32 s5, s57, 0
	global_load_lds_dwordx4 v162, s[4:5]
	s_add_u32 m0, s62, 0x5000
	s_add_u32 s4, s56, 0x140000
	s_addc_u32 s5, s57, 0
	global_load_lds_dwordx4 v162, s[4:5]
	s_add_u32 m0, s62, 0x6000
	s_add_u32 s4, s56, 0x180000
	s_addc_u32 s5, s57, 0
	global_load_lds_dwordx4 v162, s[4:5]
	s_add_u32 m0, s62, 0x7000
	s_add_u32 s4, s56, 0x1c0000
	s_addc_u32 s5, s57, 0
	global_load_lds_dwordx4 v162, s[4:5]
	s_cmp_gt_u32 s70, 1
	s_cbranch_scc1 .Lg2_ff2_nodma_2
	s_add_u32 m0, s62, 0x8000
	s_add_u32 s4, s56, 0x200000
	s_addc_u32 s5, s57, 0
	global_load_lds_dwordx4 v162, s[4:5]
.Lg2_ff2_nodma_2:
.Lg2_ff2_nd17_0:
	v_mfma_f32_16x16x32_bf16 v[96:99], v[188:191], v[164:167], v[96:99]
	v_mfma_f32_16x16x32_bf16 v[100:103], v[196:199], v[164:167], v[100:103]
	v_mfma_f32_16x16x32_bf16 v[104:107], v[188:191], v[168:171], v[104:107]
	v_mfma_f32_16x16x32_bf16 v[108:111], v[196:199], v[168:171], v[108:111]
	v_mfma_f32_16x16x32_bf16 v[112:115], v[188:191], v[172:175], v[112:115]
	v_mfma_f32_16x16x32_bf16 v[116:119], v[196:199], v[172:175], v[116:119]
	v_mfma_f32_16x16x32_bf16 v[120:123], v[188:191], v[176:179], v[120:123]
	v_mfma_f32_16x16x32_bf16 v[124:127], v[196:199], v[176:179], v[124:127]
	v_mfma_f32_16x16x32_bf16 v[128:131], v[188:191], v[180:183], v[128:131]
	v_mfma_f32_16x16x32_bf16 v[132:135], v[196:199], v[180:183], v[132:135]
	s_cmp_ge_u32 s63, 62
	s_cbranch_scc1 .Lg2_ff2_nb17_1
	s_add_u32 s58, s58, 0x800
	s_addc_u32 s59, s59, 0
	global_load_dwordx4 v[184:187], v160, s[58:59] offset:0
	global_load_dwordx4 v[188:191], v160, s[58:59] offset:1024
	global_load_dwordx4 v[192:195], v161, s[58:59] offset:0
	global_load_dwordx4 v[196:199], v161, s[58:59] offset:1024
.Lg2_ff2_nb17_1:
	ds_read_b128 v[164:167], v158 offset:8192
	ds_read_b128 v[168:171], v158 offset:10240
	ds_read_b128 v[172:175], v158 offset:12288
	ds_read_b128 v[176:179], v158 offset:14336
	s_waitcnt lgkmcnt(4)
	v_mfma_f32_16x16x32_bf16 v[0:3], v[200:203], v[136:139], v[0:3]
	v_mfma_f32_16x16x32_bf16 v[4:7], v[208:211], v[136:139], v[4:7]
	v_mfma_f32_16x16x32_bf16 v[8:11], v[200:203], v[140:143], v[8:11]
	v_mfma_f32_16x16x32_bf16 v[12:15], v[208:211], v[140:143], v[12:15]
	v_mfma_f32_16x16x32_bf16 v[16:19], v[200:203], v[144:147], v[16:19]
	v_mfma_f32_16x16x32_bf16 v[20:23], v[208:211], v[144:147], v[20:23]
	v_mfma_f32_16x16x32_bf16 v[24:27], v[200:203], v[148:151], v[24:27]
	v_mfma_f32_16x16x32_bf16 v[28:31], v[208:211], v[148:151], v[28:31]
	ds_read_b128 v[136:139], v158 offset:16384
	ds_read_b128 v[140:143], v158 offset:18432
	ds_read_b128 v[144:147], v158 offset:20480
	ds_read_b128 v[148:151], v158 offset:22528
	s_waitcnt lgkmcnt(4)
	v_mfma_f32_16x16x32_bf16 v[32:35], v[200:203], v[164:167], v[32:35]
	v_mfma_f32_16x16x32_bf16 v[36:39], v[208:211], v[164:167], v[36:39]
	v_mfma_f32_16x16x32_bf16 v[40:43], v[200:203], v[168:171], v[40:43]
	v_mfma_f32_16x16x32_bf16 v[44:47], v[208:211], v[168:171], v[44:47]
	v_mfma_f32_16x16x32_bf16 v[48:51], v[200:203], v[172:175], v[48:51]
	v_mfma_f32_16x16x32_bf16 v[52:55], v[208:211], v[172:175], v[52:55]
	v_mfma_f32_16x16x32_bf16 v[56:59], v[200:203], v[176:179], v[56:59]
	v_mfma_f32_16x16x32_bf16 v[60:63], v[208:211], v[176:179], v[60:63]
	ds_read_b128 v[164:167], v158 offset:24576
	ds_read_b128 v[168:171], v158 offset:26624
	ds_read_b128 v[172:175], v158 offset:28672
	ds_read_b128 v[176:179], v158 offset:30720
	ds_read_b128 v[180:183], v158 offset:32768
	s_waitcnt lgkmcnt(5)
	v_mfma_f32_16x16x32_bf16 v[64:67], v[200:203], v[136:139], v[64:67]
	v_mfma_f32_16x16x32_bf16 v[68:71], v[208:211], v[136:139], v[68:71]
	v_mfma_f32_16x16x32_bf16 v[72:75], v[200:203], v[140:143], v[72:75]
	v_mfma_f32_16x16x32_bf16 v[76:79], v[208:211], v[140:143], v[76:79]
	v_mfma_f32_16x16x32_bf16 v[80:83], v[200:203], v[144:147], v[80:83]
	v_mfma_f32_16x16x32_bf16 v[84:87], v[208:211], v[144:147], v[84:87]
	v_mfma_f32_16x16x32_bf16 v[88:91], v[200:203], v[148:151], v[88:91]
	v_mfma_f32_16x16x32_bf16 v[92:95], v[208:211], v[148:151], v[92:95]
	ds_read_b128 v[136:139], v159 offset:0
	ds_read_b128 v[140:143], v159 offset:2048
	ds_read_b128 v[144:147], v159 offset:4096
	ds_read_b128 v[148:151], v159 offset:6144
	s_waitcnt lgkmcnt(4)
	v_mfma_f32_16x16x32_bf16 v[96:99], v[200:203], v[164:167], v[96:99]
	v_mfma_f32_16x16x32_bf16 v[100:103], v[208:211], v[164:167], v[100:103]
	v_mfma_f32_16x16x32_bf16 v[104:107], v[200:203], v[168:171], v[104:107]
	v_mfma_f32_16x16x32_bf16 v[108:111], v[208:211], v[168:171], v[108:111]
	v_mfma_f32_16x16x32_bf16 v[112:115], v[200:203], v[172:175], v[112:115]
	v_mfma_f32_16x16x32_bf16 v[116:119], v[208:211], v[172:175], v[116:119]
	v_mfma_f32_16x16x32_bf16 v[120:123], v[200:203], v[176:179], v[120:123]
	v_mfma_f32_16x16x32_bf16 v[124:127], v[208:211], v[176:179], v[124:127]
	v_mfma_f32_16x16x32_bf16 v[128:131], v[200:203], v[180:183], v[128:131]
	v_mfma_f32_16x16x32_bf16 v[132:135], v[208:211], v[180:183], v[132:135]
	ds_read_b128 v[164:167], v159 offset:8192
	ds_read_b128 v[168:171], v159 offset:10240
	ds_read_b128 v[172:175], v159 offset:12288
	ds_read_b128 v[176:179], v159 offset:14336
	s_waitcnt lgkmcnt(4)
	v_mfma_f32_16x16x32_bf16 v[0:3], v[204:207], v[136:139], v[0:3]
	v_mfma_f32_16x16x32_bf16 v[4:7], v[240:243], v[136:139], v[4:7]
	v_mfma_f32_16x16x32_bf16 v[8:11], v[204:207], v[140:143], v[8:11]
	v_mfma_f32_16x16x32_bf16 v[12:15], v[240:243], v[140:143], v[12:15]
	v_mfma_f32_16x16x32_bf16 v[16:19], v[204:207], v[144:147], v[16:19]
	v_mfma_f32_16x16x32_bf16 v[20:23], v[240:243], v[144:147], v[20:23]
	v_mfma_f32_16x16x32_bf16 v[24:27], v[204:207], v[148:151], v[24:27]
	v_mfma_f32_16x16x32_bf16 v[28:31], v[240:243], v[148:151], v[28:31]
	ds_read_b128 v[136:139], v159 offset:16384
	ds_read_b128 v[140:143], v159 offset:18432
	ds_read_b128 v[144:147], v159 offset:20480
	ds_read_b128 v[148:151], v159 offset:22528
	s_waitcnt lgkmcnt(4)
	v_mfma_f32_16x16x32_bf16 v[32:35], v[204:207], v[164:167], v[32:35]
	v_mfma_f32_16x16x32_bf16 v[36:39], v[240:243], v[164:167], v[36:39]
	v_mfma_f32_16x16x32_bf16 v[40:43], v[204:207], v[168:171], v[40:43]
	v_mfma_f32_16x16x32_bf16 v[44:47], v[240:243], v[168:171], v[44:47]
	v_mfma_f32_16x16x32_bf16 v[48:51], v[204:207], v[172:175], v[48:51]
	v_mfma_f32_16x16x32_bf16 v[52:55], v[240:243], v[172:175], v[52:55]
	v_mfma_f32_16x16x32_bf16 v[56:59], v[204:207], v[176:179], v[56:59]
	v_mfma_f32_16x16x32_bf16 v[60:63], v[240:243], v[176:179], v[60:63]
	ds_read_b128 v[164:167], v159 offset:24576
	ds_read_b128 v[168:171], v159 offset:26624
	ds_read_b128 v[172:175], v159 offset:28672
	ds_read_b128 v[176:179], v159 offset:30720
	ds_read_b128 v[180:183], v159 offset:32768
	s_waitcnt lgkmcnt(5)
	v_mfma_f32_16x16x32_bf16 v[64:67], v[204:207], v[136:139], v[64:67]
	v_mfma_f32_16x16x32_bf16 v[68:71], v[240:243], v[136:139], v[68:71]
	v_mfma_f32_16x16x32_bf16 v[72:75], v[204:207], v[140:143], v[72:75]
	v_mfma_f32_16x16x32_bf16 v[76:79], v[240:243], v[140:143], v[76:79]
	v_mfma_f32_16x16x32_bf16 v[80:83], v[204:207], v[144:147], v[80:83]
	v_mfma_f32_16x16x32_bf16 v[84:87], v[240:243], v[144:147], v[84:87]
	v_mfma_f32_16x16x32_bf16 v[88:91], v[204:207], v[148:151], v[88:91]
	v_mfma_f32_16x16x32_bf16 v[92:95], v[240:243], v[148:151], v[92:95]
	s_waitcnt vmcnt(0) lgkmcnt(0)
	s_barrier
	s_cmp_ge_u32 s63, 62
	s_cbranch_scc1 .Lg2_ff2_nd17_1
	ds_read_b128 v[136:139], v156 offset:0
	ds_read_b128 v[140:143], v156 offset:2048
	ds_read_b128 v[144:147], v156 offset:4096
	ds_read_b128 v[148:151], v156 offset:6144
	s_add_u32 s56, s56, 0x80
	s_addc_u32 s57, s57, 0
	s_add_u32 m0, s62, 0x8800
	s_add_u32 s4, s56, 0x0
	s_addc_u32 s5, s57, 0
	global_load_lds_dwordx4 v162, s[4:5]
	s_add_u32 m0, s62, 0x9800
	s_add_u32 s4, s56, 0x40000
	s_addc_u32 s5, s57, 0
	global_load_lds_dwordx4 v162, s[4:5]
	s_add_u32 m0, s62, 0xa800
	s_add_u32 s4, s56, 0x80000
	s_addc_u32 s5, s57, 0
	global_load_lds_dwordx4 v162, s[4:5]
	s_add_u32 m0, s62, 0xb800
	s_add_u32 s4, s56, 0xc0000
	s_addc_u32 s5, s57, 0
	global_load_lds_dwordx4 v162, s[4:5]
	s_add_u32 m0, s62, 0xc800
	s_add_u32 s4, s56, 0x100000
	s_addc_u32 s5, s57, 0
	global_load_lds_dwordx4 v162, s[4:5]
	s_add_u32 m0, s62, 0xd800
	s_add_u32 s4, s56, 0x140000
	s_addc_u32 s5, s57, 0
	global_load_lds_dwordx4 v162, s[4:5]
	s_add_u32 m0, s62, 0xe800
	s_add_u32 s4, s56, 0x180000
	s_addc_u32 s5, s57, 0
	global_load_lds_dwordx4 v162, s[4:5]
	s_add_u32 m0, s62, 0xf800
	s_add_u32 s4, s56, 0x1c0000
	s_addc_u32 s5, s57, 0
	global_load_lds_dwordx4 v162, s[4:5]
	s_cmp_gt_u32 s70, 1
	s_cbranch_scc1 .Lg2_ff2_nodma_3
	s_add_u32 m0, s62, 0x10800
	s_add_u32 s4, s56, 0x200000
	s_addc_u32 s5, s57, 0
	global_load_lds_dwordx4 v162, s[4:5]
.Lg2_ff2_nodma_3:
.Lg2_ff2_nd17_1:
	v_mfma_f32_16x16x32_bf16 v[96:99], v[204:207], v[164:167], v[96:99]
	v_mfma_f32_16x16x32_bf16 v[100:103], v[240:243], v[164:167], v[100:103]
	v_mfma_f32_16x16x32_bf16 v[104:107], v[204:207], v[168:171], v[104:107]
	v_mfma_f32_16x16x32_bf16 v[108:111], v[240:243], v[168:171], v[108:111]
	v_mfma_f32_16x16x32_bf16 v[112:115], v[204:207], v[172:175], v[112:115]
	v_mfma_f32_16x16x32_bf16 v[116:119], v[240:243], v[172:175], v[116:119]
	v_mfma_f32_16x16x32_bf16 v[120:123], v[204:207], v[176:179], v[120:123]
	v_mfma_f32_16x16x32_bf16 v[124:127], v[240:243], v[176:179], v[124:127]
	v_mfma_f32_16x16x32_bf16 v[128:131], v[204:207], v[180:183], v[128:131]
	v_mfma_f32_16x16x32_bf16 v[132:135], v[240:243], v[180:183], v[132:135]
	s_add_i32 s63, s63, 2
	s_cmp_lt_u32 s63, 64
	s_cbranch_scc1 .Lg2_ff2_loop17
	s_branch .Lg2_ff2_episel

.Lg2_ff2_loop16:
	s_add_u32 s58, s58, 0x800
	s_addc_u32 s59, s59, 0
	global_load_dwordx4 v[200:203], v160, s[58:59] offset:0
	global_load_dwordx4 v[204:207], v160, s[58:59] offset:1024
	global_load_dwordx4 v[208:211], v161, s[58:59] offset:0
	global_load_dwordx4 v[240:243], v161, s[58:59] offset:1024
	ds_read_b128 v[164:167], v156 offset:8192
	ds_read_b128 v[168:171], v156 offset:10240
	ds_read_b128 v[172:175], v156 offset:12288
	ds_read_b128 v[176:179], v156 offset:14336
	s_waitcnt lgkmcnt(4)
	v_mfma_f32_16x16x32_bf16 v[0:3], v[184:187], v[136:139], v[0:3]
	v_mfma_f32_16x16x32_bf16 v[4:7], v[192:195], v[136:139], v[4:7]
	v_mfma_f32_16x16x32_bf16 v[8:11], v[184:187], v[140:143], v[8:11]
	v_mfma_f32_16x16x32_bf16 v[12:15], v[192:195], v[140:143], v[12:15]
	v_mfma_f32_16x16x32_bf16 v[16:19], v[184:187], v[144:147], v[16:19]
	v_mfma_f32_16x16x32_bf16 v[20:23], v[192:195], v[144:147], v[20:23]
	v_mfma_f32_16x16x32_bf16 v[24:27], v[184:187], v[148:151], v[24:27]
	v_mfma_f32_16x16x32_bf16 v[28:31], v[192:195], v[148:151], v[28:31]
	ds_read_b128 v[136:139], v156 offset:16384
	ds_read_b128 v[140:143], v156 offset:18432
	ds_read_b128 v[144:147], v156 offset:20480
	ds_read_b128 v[148:151], v156 offset:22528
	s_waitcnt lgkmcnt(4)
	v_mfma_f32_16x16x32_bf16 v[32:35], v[184:187], v[164:167], v[32:35]
	v_mfma_f32_16x16x32_bf16 v[36:39], v[192:195], v[164:167], v[36:39]
	v_mfma_f32_16x16x32_bf16 v[40:43], v[184:187], v[168:171], v[40:43]
	v_mfma_f32_16x16x32_bf16 v[44:47], v[192:195], v[168:171], v[44:47]
	v_mfma_f32_16x16x32_bf16 v[48:51], v[184:187], v[172:175], v[48:51]
	v_mfma_f32_16x16x32_bf16 v[52:55], v[192:195], v[172:175], v[52:55]
	v_mfma_f32_16x16x32_bf16 v[56:59], v[184:187], v[176:179], v[56:59]
	v_mfma_f32_16x16x32_bf16 v[60:63], v[192:195], v[176:179], v[60:63]
	ds_read_b128 v[164:167], v156 offset:24576
	ds_read_b128 v[168:171], v156 offset:26624
	ds_read_b128 v[172:175], v156 offset:28672
	ds_read_b128 v[176:179], v156 offset:30720
	s_waitcnt lgkmcnt(4)
	v_mfma_f32_16x16x32_bf16 v[64:67], v[184:187], v[136:139], v[64:67]
	v_mfma_f32_16x16x32_bf16 v[68:71], v[192:195], v[136:139], v[68:71]
	v_mfma_f32_16x16x32_bf16 v[72:75], v[184:187], v[140:143], v[72:75]
	v_mfma_f32_16x16x32_bf16 v[76:79], v[192:195], v[140:143], v[76:79]
	v_mfma_f32_16x16x32_bf16 v[80:83], v[184:187], v[144:147], v[80:83]
	v_mfma_f32_16x16x32_bf16 v[84:87], v[192:195], v[144:147], v[84:87]
	v_mfma_f32_16x16x32_bf16 v[88:91], v[184:187], v[148:151], v[88:91]
	v_mfma_f32_16x16x32_bf16 v[92:95], v[192:195], v[148:151], v[92:95]
	ds_read_b128 v[136:139], v157 offset:0
	ds_read_b128 v[140:143], v157 offset:2048
	ds_read_b128 v[144:147], v157 offset:4096
	ds_read_b128 v[148:151], v157 offset:6144
	s_waitcnt lgkmcnt(4)
	v_mfma_f32_16x16x32_bf16 v[96:99], v[184:187], v[164:167], v[96:99]
	v_mfma_f32_16x16x32_bf16 v[100:103], v[192:195], v[164:167], v[100:103]
	v_mfma_f32_16x16x32_bf16 v[104:107], v[184:187], v[168:171], v[104:107]
	v_mfma_f32_16x16x32_bf16 v[108:111], v[192:195], v[168:171], v[108:111]
	v_mfma_f32_16x16x32_bf16 v[112:115], v[184:187], v[172:175], v[112:115]
	v_mfma_f32_16x16x32_bf16 v[116:119], v[192:195], v[172:175], v[116:119]
	v_mfma_f32_16x16x32_bf16 v[120:123], v[184:187], v[176:179], v[120:123]
	v_mfma_f32_16x16x32_bf16 v[124:127], v[192:195], v[176:179], v[124:127]
	ds_read_b128 v[164:167], v157 offset:8192
	ds_read_b128 v[168:171], v157 offset:10240
	ds_read_b128 v[172:175], v157 offset:12288
	ds_read_b128 v[176:179], v157 offset:14336
	s_waitcnt lgkmcnt(4)
	v_mfma_f32_16x16x32_bf16 v[0:3], v[188:191], v[136:139], v[0:3]
	v_mfma_f32_16x16x32_bf16 v[4:7], v[196:199], v[136:139], v[4:7]
	v_mfma_f32_16x16x32_bf16 v[8:11], v[188:191], v[140:143], v[8:11]
	v_mfma_f32_16x16x32_bf16 v[12:15], v[196:199], v[140:143], v[12:15]
	v_mfma_f32_16x16x32_bf16 v[16:19], v[188:191], v[144:147], v[16:19]
	v_mfma_f32_16x16x32_bf16 v[20:23], v[196:199], v[144:147], v[20:23]
	v_mfma_f32_16x16x32_bf16 v[24:27], v[188:191], v[148:151], v[24:27]
	v_mfma_f32_16x16x32_bf16 v[28:31], v[196:199], v[148:151], v[28:31]
	ds_read_b128 v[136:139], v157 offset:16384
	ds_read_b128 v[140:143], v157 offset:18432
	ds_read_b128 v[144:147], v157 offset:20480
	ds_read_b128 v[148:151], v157 offset:22528
	s_waitcnt lgkmcnt(4)
	v_mfma_f32_16x16x32_bf16 v[32:35], v[188:191], v[164:167], v[32:35]
	v_mfma_f32_16x16x32_bf16 v[36:39], v[196:199], v[164:167], v[36:39]
	v_mfma_f32_16x16x32_bf16 v[40:43], v[188:191], v[168:171], v[40:43]
	v_mfma_f32_16x16x32_bf16 v[44:47], v[196:199], v[168:171], v[44:47]
	v_mfma_f32_16x16x32_bf16 v[48:51], v[188:191], v[172:175], v[48:51]
	v_mfma_f32_16x16x32_bf16 v[52:55], v[196:199], v[172:175], v[52:55]
	v_mfma_f32_16x16x32_bf16 v[56:59], v[188:191], v[176:179], v[56:59]
	v_mfma_f32_16x16x32_bf16 v[60:63], v[196:199], v[176:179], v[60:63]
	ds_read_b128 v[164:167], v157 offset:24576
	ds_read_b128 v[168:171], v157 offset:26624
	ds_read_b128 v[172:175], v157 offset:28672
	ds_read_b128 v[176:179], v157 offset:30720
	s_waitcnt lgkmcnt(4)
	v_mfma_f32_16x16x32_bf16 v[64:67], v[188:191], v[136:139], v[64:67]
	v_mfma_f32_16x16x32_bf16 v[68:71], v[196:199], v[136:139], v[68:71]
	v_mfma_f32_16x16x32_bf16 v[72:75], v[188:191], v[140:143], v[72:75]
	v_mfma_f32_16x16x32_bf16 v[76:79], v[196:199], v[140:143], v[76:79]
	v_mfma_f32_16x16x32_bf16 v[80:83], v[188:191], v[144:147], v[80:83]
	v_mfma_f32_16x16x32_bf16 v[84:87], v[196:199], v[144:147], v[84:87]
	v_mfma_f32_16x16x32_bf16 v[88:91], v[188:191], v[148:151], v[88:91]
	v_mfma_f32_16x16x32_bf16 v[92:95], v[196:199], v[148:151], v[92:95]
	s_waitcnt vmcnt(0) lgkmcnt(0)
	s_barrier
	ds_read_b128 v[136:139], v158 offset:0
	ds_read_b128 v[140:143], v158 offset:2048
	ds_read_b128 v[144:147], v158 offset:4096
	ds_read_b128 v[148:151], v158 offset:6144
	s_cmp_ge_u32 s63, 62
	s_cbranch_scc1 .Lg2_ff2_nd16_0
	s_add_u32 s56, s56, 0x80
	s_addc_u32 s57, s57, 0
	s_add_u32 m0, s62, 0x0
	s_add_u32 s4, s56, 0x0
	s_addc_u32 s5, s57, 0
	global_load_lds_dwordx4 v162, s[4:5]
	s_add_u32 m0, s62, 0x1000
	s_add_u32 s4, s56, 0x40000
	s_addc_u32 s5, s57, 0
	global_load_lds_dwordx4 v162, s[4:5]
	s_add_u32 m0, s62, 0x2000
	s_add_u32 s4, s56, 0x80000
	s_addc_u32 s5, s57, 0
	global_load_lds_dwordx4 v162, s[4:5]
	s_add_u32 m0, s62, 0x3000
	s_add_u32 s4, s56, 0xc0000
	s_addc_u32 s5, s57, 0
	global_load_lds_dwordx4 v162, s[4:5]
	s_add_u32 m0, s62, 0x4000
	s_add_u32 s4, s56, 0x100000
	s_addc_u32 s5, s57, 0
	global_load_lds_dwordx4 v162, s[4:5]
	s_add_u32 m0, s62, 0x5000
	s_add_u32 s4, s56, 0x140000
	s_addc_u32 s5, s57, 0
	global_load_lds_dwordx4 v162, s[4:5]
	s_add_u32 m0, s62, 0x6000
	s_add_u32 s4, s56, 0x180000
	s_addc_u32 s5, s57, 0
	global_load_lds_dwordx4 v162, s[4:5]
	s_add_u32 m0, s62, 0x7000
	s_add_u32 s4, s56, 0x1c0000
	s_addc_u32 s5, s57, 0
	global_load_lds_dwordx4 v162, s[4:5]
.Lg2_ff2_nd16_0:
	v_mfma_f32_16x16x32_bf16 v[96:99], v[188:191], v[164:167], v[96:99]
	v_mfma_f32_16x16x32_bf16 v[100:103], v[196:199], v[164:167], v[100:103]
	v_mfma_f32_16x16x32_bf16 v[104:107], v[188:191], v[168:171], v[104:107]
	v_mfma_f32_16x16x32_bf16 v[108:111], v[196:199], v[168:171], v[108:111]
	v_mfma_f32_16x16x32_bf16 v[112:115], v[188:191], v[172:175], v[112:115]
	v_mfma_f32_16x16x32_bf16 v[116:119], v[196:199], v[172:175], v[116:119]
	v_mfma_f32_16x16x32_bf16 v[120:123], v[188:191], v[176:179], v[120:123]
	v_mfma_f32_16x16x32_bf16 v[124:127], v[196:199], v[176:179], v[124:127]
	s_cmp_ge_u32 s63, 62
	s_cbranch_scc1 .Lg2_ff2_nb16_1
	s_add_u32 s58, s58, 0x800
	s_addc_u32 s59, s59, 0
	global_load_dwordx4 v[184:187], v160, s[58:59] offset:0
	global_load_dwordx4 v[188:191], v160, s[58:59] offset:1024
	global_load_dwordx4 v[192:195], v161, s[58:59] offset:0
	global_load_dwordx4 v[196:199], v161, s[58:59] offset:1024
.Lg2_ff2_nb16_1:
	ds_read_b128 v[164:167], v158 offset:8192
	ds_read_b128 v[168:171], v158 offset:10240
	ds_read_b128 v[172:175], v158 offset:12288
	ds_read_b128 v[176:179], v158 offset:14336
	s_waitcnt lgkmcnt(4)
	v_mfma_f32_16x16x32_bf16 v[0:3], v[200:203], v[136:139], v[0:3]
	v_mfma_f32_16x16x32_bf16 v[4:7], v[208:211], v[136:139], v[4:7]
	v_mfma_f32_16x16x32_bf16 v[8:11], v[200:203], v[140:143], v[8:11]
	v_mfma_f32_16x16x32_bf16 v[12:15], v[208:211], v[140:143], v[12:15]
	v_mfma_f32_16x16x32_bf16 v[16:19], v[200:203], v[144:147], v[16:19]
	v_mfma_f32_16x16x32_bf16 v[20:23], v[208:211], v[144:147], v[20:23]
	v_mfma_f32_16x16x32_bf16 v[24:27], v[200:203], v[148:151], v[24:27]
	v_mfma_f32_16x16x32_bf16 v[28:31], v[208:211], v[148:151], v[28:31]
	ds_read_b128 v[136:139], v158 offset:16384
	ds_read_b128 v[140:143], v158 offset:18432
	ds_read_b128 v[144:147], v158 offset:20480
	ds_read_b128 v[148:151], v158 offset:22528
	s_waitcnt lgkmcnt(4)
	v_mfma_f32_16x16x32_bf16 v[32:35], v[200:203], v[164:167], v[32:35]
	v_mfma_f32_16x16x32_bf16 v[36:39], v[208:211], v[164:167], v[36:39]
	v_mfma_f32_16x16x32_bf16 v[40:43], v[200:203], v[168:171], v[40:43]
	v_mfma_f32_16x16x32_bf16 v[44:47], v[208:211], v[168:171], v[44:47]
	v_mfma_f32_16x16x32_bf16 v[48:51], v[200:203], v[172:175], v[48:51]
	v_mfma_f32_16x16x32_bf16 v[52:55], v[208:211], v[172:175], v[52:55]
	v_mfma_f32_16x16x32_bf16 v[56:59], v[200:203], v[176:179], v[56:59]
	v_mfma_f32_16x16x32_bf16 v[60:63], v[208:211], v[176:179], v[60:63]
	ds_read_b128 v[164:167], v158 offset:24576
	ds_read_b128 v[168:171], v158 offset:26624
	ds_read_b128 v[172:175], v158 offset:28672
	ds_read_b128 v[176:179], v158 offset:30720
	s_waitcnt lgkmcnt(4)
	v_mfma_f32_16x16x32_bf16 v[64:67], v[200:203], v[136:139], v[64:67]
	v_mfma_f32_16x16x32_bf16 v[68:71], v[208:211], v[136:139], v[68:71]
	v_mfma_f32_16x16x32_bf16 v[72:75], v[200:203], v[140:143], v[72:75]
	v_mfma_f32_16x16x32_bf16 v[76:79], v[208:211], v[140:143], v[76:79]
	v_mfma_f32_16x16x32_bf16 v[80:83], v[200:203], v[144:147], v[80:83]
	v_mfma_f32_16x16x32_bf16 v[84:87], v[208:211], v[144:147], v[84:87]
	v_mfma_f32_16x16x32_bf16 v[88:91], v[200:203], v[148:151], v[88:91]
	v_mfma_f32_16x16x32_bf16 v[92:95], v[208:211], v[148:151], v[92:95]
	ds_read_b128 v[136:139], v159 offset:0
	ds_read_b128 v[140:143], v159 offset:2048
	ds_read_b128 v[144:147], v159 offset:4096
	ds_read_b128 v[148:151], v159 offset:6144
	s_waitcnt lgkmcnt(4)
	v_mfma_f32_16x16x32_bf16 v[96:99], v[200:203], v[164:167], v[96:99]
	v_mfma_f32_16x16x32_bf16 v[100:103], v[208:211], v[164:167], v[100:103]
	v_mfma_f32_16x16x32_bf16 v[104:107], v[200:203], v[168:171], v[104:107]
	v_mfma_f32_16x16x32_bf16 v[108:111], v[208:211], v[168:171], v[108:111]
	v_mfma_f32_16x16x32_bf16 v[112:115], v[200:203], v[172:175], v[112:115]
	v_mfma_f32_16x16x32_bf16 v[116:119], v[208:211], v[172:175], v[116:119]
	v_mfma_f32_16x16x32_bf16 v[120:123], v[200:203], v[176:179], v[120:123]
	v_mfma_f32_16x16x32_bf16 v[124:127], v[208:211], v[176:179], v[124:127]
	ds_read_b128 v[164:167], v159 offset:8192
	ds_read_b128 v[168:171], v159 offset:10240
	ds_read_b128 v[172:175], v159 offset:12288
	ds_read_b128 v[176:179], v159 offset:14336
	s_waitcnt lgkmcnt(4)
	v_mfma_f32_16x16x32_bf16 v[0:3], v[204:207], v[136:139], v[0:3]
	v_mfma_f32_16x16x32_bf16 v[4:7], v[240:243], v[136:139], v[4:7]
	v_mfma_f32_16x16x32_bf16 v[8:11], v[204:207], v[140:143], v[8:11]
	v_mfma_f32_16x16x32_bf16 v[12:15], v[240:243], v[140:143], v[12:15]
	v_mfma_f32_16x16x32_bf16 v[16:19], v[204:207], v[144:147], v[16:19]
	v_mfma_f32_16x16x32_bf16 v[20:23], v[240:243], v[144:147], v[20:23]
	v_mfma_f32_16x16x32_bf16 v[24:27], v[204:207], v[148:151], v[24:27]
	v_mfma_f32_16x16x32_bf16 v[28:31], v[240:243], v[148:151], v[28:31]
	ds_read_b128 v[136:139], v159 offset:16384
	ds_read_b128 v[140:143], v159 offset:18432
	ds_read_b128 v[144:147], v159 offset:20480
	ds_read_b128 v[148:151], v159 offset:22528
	s_waitcnt lgkmcnt(4)
	v_mfma_f32_16x16x32_bf16 v[32:35], v[204:207], v[164:167], v[32:35]
	v_mfma_f32_16x16x32_bf16 v[36:39], v[240:243], v[164:167], v[36:39]
	v_mfma_f32_16x16x32_bf16 v[40:43], v[204:207], v[168:171], v[40:43]
	v_mfma_f32_16x16x32_bf16 v[44:47], v[240:243], v[168:171], v[44:47]
	v_mfma_f32_16x16x32_bf16 v[48:51], v[204:207], v[172:175], v[48:51]
	v_mfma_f32_16x16x32_bf16 v[52:55], v[240:243], v[172:175], v[52:55]
	v_mfma_f32_16x16x32_bf16 v[56:59], v[204:207], v[176:179], v[56:59]
	v_mfma_f32_16x16x32_bf16 v[60:63], v[240:243], v[176:179], v[60:63]
	ds_read_b128 v[164:167], v159 offset:24576
	ds_read_b128 v[168:171], v159 offset:26624
	ds_read_b128 v[172:175], v159 offset:28672
	ds_read_b128 v[176:179], v159 offset:30720
	s_waitcnt lgkmcnt(4)
	v_mfma_f32_16x16x32_bf16 v[64:67], v[204:207], v[136:139], v[64:67]
	v_mfma_f32_16x16x32_bf16 v[68:71], v[240:243], v[136:139], v[68:71]
	v_mfma_f32_16x16x32_bf16 v[72:75], v[204:207], v[140:143], v[72:75]
	v_mfma_f32_16x16x32_bf16 v[76:79], v[240:243], v[140:143], v[76:79]
	v_mfma_f32_16x16x32_bf16 v[80:83], v[204:207], v[144:147], v[80:83]
	v_mfma_f32_16x16x32_bf16 v[84:87], v[240:243], v[144:147], v[84:87]
	v_mfma_f32_16x16x32_bf16 v[88:91], v[204:207], v[148:151], v[88:91]
	v_mfma_f32_16x16x32_bf16 v[92:95], v[240:243], v[148:151], v[92:95]
	s_waitcnt vmcnt(0) lgkmcnt(0)
	s_barrier
	s_cmp_ge_u32 s63, 62
	s_cbranch_scc1 .Lg2_ff2_nd16_1
	ds_read_b128 v[136:139], v156 offset:0
	ds_read_b128 v[140:143], v156 offset:2048
	ds_read_b128 v[144:147], v156 offset:4096
	ds_read_b128 v[148:151], v156 offset:6144
	s_add_u32 s56, s56, 0x80
	s_addc_u32 s57, s57, 0
	s_add_u32 m0, s62, 0x8800
	s_add_u32 s4, s56, 0x0
	s_addc_u32 s5, s57, 0
	global_load_lds_dwordx4 v162, s[4:5]
	s_add_u32 m0, s62, 0x9800
	s_add_u32 s4, s56, 0x40000
	s_addc_u32 s5, s57, 0
	global_load_lds_dwordx4 v162, s[4:5]
	s_add_u32 m0, s62, 0xa800
	s_add_u32 s4, s56, 0x80000
	s_addc_u32 s5, s57, 0
	global_load_lds_dwordx4 v162, s[4:5]
	s_add_u32 m0, s62, 0xb800
	s_add_u32 s4, s56, 0xc0000
	s_addc_u32 s5, s57, 0
	global_load_lds_dwordx4 v162, s[4:5]
	s_add_u32 m0, s62, 0xc800
	s_add_u32 s4, s56, 0x100000
	s_addc_u32 s5, s57, 0
	global_load_lds_dwordx4 v162, s[4:5]
	s_add_u32 m0, s62, 0xd800
	s_add_u32 s4, s56, 0x140000
	s_addc_u32 s5, s57, 0
	global_load_lds_dwordx4 v162, s[4:5]
	s_add_u32 m0, s62, 0xe800
	s_add_u32 s4, s56, 0x180000
	s_addc_u32 s5, s57, 0
	global_load_lds_dwordx4 v162, s[4:5]
	s_add_u32 m0, s62, 0xf800
	s_add_u32 s4, s56, 0x1c0000
	s_addc_u32 s5, s57, 0
	global_load_lds_dwordx4 v162, s[4:5]

.Lg2_ff1_loop17:
	s_add_u32 s58, s58, 0x800
	s_addc_u32 s59, s59, 0
	global_load_dwordx4 v[200:203], v160, s[58:59] offset:0
	global_load_dwordx4 v[204:207], v160, s[58:59] offset:1024
	global_load_dwordx4 v[208:211], v161, s[58:59] offset:0
	global_load_dwordx4 v[240:243], v161, s[58:59] offset:1024
	ds_read_b128 v[164:167], v156 offset:8192
	ds_read_b128 v[168:171], v156 offset:10240
	ds_read_b128 v[172:175], v156 offset:12288
	ds_read_b128 v[176:179], v156 offset:14336
	s_waitcnt lgkmcnt(4)
	v_mfma_f32_16x16x32_bf16 v[0:3], v[184:187], v[136:139], v[0:3]
	v_mfma_f32_16x16x32_bf16 v[4:7], v[192:195], v[136:139], v[4:7]
	v_mfma_f32_16x16x32_bf16 v[8:11], v[184:187], v[140:143], v[8:11]
	v_mfma_f32_16x16x32_bf16 v[12:15], v[192:195], v[140:143], v[12:15]
	v_mfma_f32_16x16x32_bf16 v[16:19], v[184:187], v[144:147], v[16:19]
	v_mfma_f32_16x16x32_bf16 v[20:23], v[192:195], v[144:147], v[20:23]
	v_mfma_f32_16x16x32_bf16 v[24:27], v[184:187], v[148:151], v[24:27]
	v_mfma_f32_16x16x32_bf16 v[28:31], v[192:195], v[148:151], v[28:31]
	ds_read_b128 v[136:139], v156 offset:16384
	ds_read_b128 v[140:143], v156 offset:18432
	ds_read_b128 v[144:147], v156 offset:20480
	ds_read_b128 v[148:151], v156 offset:22528
	s_waitcnt lgkmcnt(4)
	v_mfma_f32_16x16x32_bf16 v[32:35], v[184:187], v[164:167], v[32:35]
	v_mfma_f32_16x16x32_bf16 v[36:39], v[192:195], v[164:167], v[36:39]
	v_mfma_f32_16x16x32_bf16 v[40:43], v[184:187], v[168:171], v[40:43]
	v_mfma_f32_16x16x32_bf16 v[44:47], v[192:195], v[168:171], v[44:47]
	v_mfma_f32_16x16x32_bf16 v[48:51], v[184:187], v[172:175], v[48:51]
	v_mfma_f32_16x16x32_bf16 v[52:55], v[192:195], v[172:175], v[52:55]
	v_mfma_f32_16x16x32_bf16 v[56:59], v[184:187], v[176:179], v[56:59]
	v_mfma_f32_16x16x32_bf16 v[60:63], v[192:195], v[176:179], v[60:63]
	ds_read_b128 v[164:167], v156 offset:24576
	ds_read_b128 v[168:171], v156 offset:26624
	ds_read_b128 v[172:175], v156 offset:28672
	ds_read_b128 v[176:179], v156 offset:30720
	ds_read_b128 v[180:183], v156 offset:32768
	s_waitcnt lgkmcnt(5)
	v_mfma_f32_16x16x32_bf16 v[64:67], v[184:187], v[136:139], v[64:67]
	v_mfma_f32_16x16x32_bf16 v[68:71], v[192:195], v[136:139], v[68:71]
	v_mfma_f32_16x16x32_bf16 v[72:75], v[184:187], v[140:143], v[72:75]
	v_mfma_f32_16x16x32_bf16 v[76:79], v[192:195], v[140:143], v[76:79]
	v_mfma_f32_16x16x32_bf16 v[80:83], v[184:187], v[144:147], v[80:83]
	v_mfma_f32_16x16x32_bf16 v[84:87], v[192:195], v[144:147], v[84:87]
	v_mfma_f32_16x16x32_bf16 v[88:91], v[184:187], v[148:151], v[88:91]
	v_mfma_f32_16x16x32_bf16 v[92:95], v[192:195], v[148:151], v[92:95]
	ds_read_b128 v[136:139], v157 offset:0
	ds_read_b128 v[140:143], v157 offset:2048
	ds_read_b128 v[144:147], v157 offset:4096
	ds_read_b128 v[148:151], v157 offset:6144
	s_waitcnt lgkmcnt(4)
	v_mfma_f32_16x16x32_bf16 v[96:99], v[184:187], v[164:167], v[96:99]
	v_mfma_f32_16x16x32_bf16 v[100:103], v[192:195], v[164:167], v[100:103]
	v_mfma_f32_16x16x32_bf16 v[104:107], v[184:187], v[168:171], v[104:107]
	v_mfma_f32_16x16x32_bf16 v[108:111], v[192:195], v[168:171], v[108:111]
	v_mfma_f32_16x16x32_bf16 v[112:115], v[184:187], v[172:175], v[112:115]
	v_mfma_f32_16x16x32_bf16 v[116:119], v[192:195], v[172:175], v[116:119]
	v_mfma_f32_16x16x32_bf16 v[120:123], v[184:187], v[176:179], v[120:123]
	v_mfma_f32_16x16x32_bf16 v[124:127], v[192:195], v[176:179], v[124:127]
	v_mfma_f32_16x16x32_bf16 v[128:131], v[184:187], v[180:183], v[128:131]
	v_mfma_f32_16x16x32_bf16 v[132:135], v[192:195], v[180:183], v[132:135]
	ds_read_b128 v[164:167], v157 offset:8192
	ds_read_b128 v[168:171], v157 offset:10240
	ds_read_b128 v[172:175], v157 offset:12288
	ds_read_b128 v[176:179], v157 offset:14336
	s_waitcnt lgkmcnt(4)
	v_mfma_f32_16x16x32_bf16 v[0:3], v[188:191], v[136:139], v[0:3]
	v_mfma_f32_16x16x32_bf16 v[4:7], v[196:199], v[136:139], v[4:7]
	v_mfma_f32_16x16x32_bf16 v[8:11], v[188:191], v[140:143], v[8:11]
	v_mfma_f32_16x16x32_bf16 v[12:15], v[196:199], v[140:143], v[12:15]
	v_mfma_f32_16x16x32_bf16 v[16:19], v[188:191], v[144:147], v[16:19]
	v_mfma_f32_16x16x32_bf16 v[20:23], v[196:199], v[144:147], v[20:23]
	v_mfma_f32_16x16x32_bf16 v[24:27], v[188:191], v[148:151], v[24:27]
	v_mfma_f32_16x16x32_bf16 v[28:31], v[196:199], v[148:151], v[28:31]
	ds_read_b128 v[136:139], v157 offset:16384
	ds_read_b128 v[140:143], v157 offset:18432
	ds_read_b128 v[144:147], v157 offset:20480
	ds_read_b128 v[148:151], v157 offset:22528
	s_waitcnt lgkmcnt(4)
	v_mfma_f32_16x16x32_bf16 v[32:35], v[188:191], v[164:167], v[32:35]
	v_mfma_f32_16x16x32_bf16 v[36:39], v[196:199], v[164:167], v[36:39]
	v_mfma_f32_16x16x32_bf16 v[40:43], v[188:191], v[168:171], v[40:43]
	v_mfma_f32_16x16x32_bf16 v[44:47], v[196:199], v[168:171], v[44:47]
	v_mfma_f32_16x16x32_bf16 v[48:51], v[188:191], v[172:175], v[48:51]
	v_mfma_f32_16x16x32_bf16 v[52:55], v[196:199], v[172:175], v[52:55]
	v_mfma_f32_16x16x32_bf16 v[56:59], v[188:191], v[176:179], v[56:59]
	v_mfma_f32_16x16x32_bf16 v[60:63], v[196:199], v[176:179], v[60:63]
	ds_read_b128 v[164:167], v157 offset:24576
	ds_read_b128 v[168:171], v157 offset:26624
	ds_read_b128 v[172:175], v157 offset:28672
	ds_read_b128 v[176:179], v157 offset:30720
	ds_read_b128 v[180:183], v157 offset:32768
	s_waitcnt lgkmcnt(5)
	v_mfma_f32_16x16x32_bf16 v[64:67], v[188:191], v[136:139], v[64:67]
	v_mfma_f32_16x16x32_bf16 v[68:71], v[196:199], v[136:139], v[68:71]
	v_mfma_f32_16x16x32_bf16 v[72:75], v[188:191], v[140:143], v[72:75]
	v_mfma_f32_16x16x32_bf16 v[76:79], v[196:199], v[140:143], v[76:79]
	v_mfma_f32_16x16x32_bf16 v[80:83], v[188:191], v[144:147], v[80:83]
	v_mfma_f32_16x16x32_bf16 v[84:87], v[196:199], v[144:147], v[84:87]
	v_mfma_f32_16x16x32_bf16 v[88:91], v[188:191], v[148:151], v[88:91]
	v_mfma_f32_16x16x32_bf16 v[92:95], v[196:199], v[148:151], v[92:95]
	s_waitcnt vmcnt(0) lgkmcnt(0)
	s_barrier
	ds_read_b128 v[136:139], v158 offset:0
	ds_read_b128 v[140:143], v158 offset:2048
	ds_read_b128 v[144:147], v158 offset:4096
	ds_read_b128 v[148:151], v158 offset:6144
	s_cmp_ge_u32 s63, 14
	s_cbranch_scc1 .Lg2_ff1_nd17_0
	s_add_u32 s56, s56, 0x80
	s_addc_u32 s57, s57, 0
	s_add_u32 m0, s62, 0x0
	s_add_u32 s4, s56, 0x0
	s_addc_u32 s5, s57, 0
	global_load_lds_dwordx4 v162, s[4:5]
	s_add_u32 m0, s62, 0x1000
	s_add_u32 s4, s56, 0x10000
	s_addc_u32 s5, s57, 0
	global_load_lds_dwordx4 v162, s[4:5]
	s_add_u32 m0, s62, 0x2000
	s_add_u32 s4, s56, 0x20000
	s_addc_u32 s5, s57, 0
	global_load_lds_dwordx4 v162, s[4:5]
	s_add_u32 m0, s62, 0x3000
	s_add_u32 s4, s56, 0x30000
	s_addc_u32 s5, s57, 0
	global_load_lds_dwordx4 v162, s[4:5]
	s_add_u32 m0, s62, 0x4000
	s_add_u32 s4, s56, 0x40000
	s_addc_u32 s5, s57, 0
	global_load_lds_dwordx4 v162, s[4:5]
	s_add_u32 m0, s62, 0x5000
	s_add_u32 s4, s56, 0x50000
	s_addc_u32 s5, s57, 0
	global_load_lds_dwordx4 v162, s[4:5]
	s_add_u32 m0, s62, 0x6000
	s_add_u32 s4, s56, 0x60000
	s_addc_u32 s5, s57, 0
	global_load_lds_dwordx4 v162, s[4:5]
	s_add_u32 m0, s62, 0x7000
	s_add_u32 s4, s56, 0x70000
	s_addc_u32 s5, s57, 0
	global_load_lds_dwordx4 v162, s[4:5]
	s_cmp_gt_u32 s70, 1
	s_cbranch_scc1 .Lg2_ff1_nodma_2
	s_add_u32 m0, s62, 0x8000
	s_add_u32 s4, s56, 0x80000
	s_addc_u32 s5, s57, 0
	global_load_lds_dwordx4 v162, s[4:5]
.Lg2_ff1_nodma_2:
.Lg2_ff1_nd17_0:
	v_mfma_f32_16x16x32_bf16 v[96:99], v[188:191], v[164:167], v[96:99]
	v_mfma_f32_16x16x32_bf16 v[100:103], v[196:199], v[164:167], v[100:103]
	v_mfma_f32_16x16x32_bf16 v[104:107], v[188:191], v[168:171], v[104:107]
	v_mfma_f32_16x16x32_bf16 v[108:111], v[196:199], v[168:171], v[108:111]
	v_mfma_f32_16x16x32_bf16 v[112:115], v[188:191], v[172:175], v[112:115]
	v_mfma_f32_16x16x32_bf16 v[116:119], v[196:199], v[172:175], v[116:119]
	v_mfma_f32_16x16x32_bf16 v[120:123], v[188:191], v[176:179], v[120:123]
	v_mfma_f32_16x16x32_bf16 v[124:127], v[196:199], v[176:179], v[124:127]
	v_mfma_f32_16x16x32_bf16 v[128:131], v[188:191], v[180:183], v[128:131]
	v_mfma_f32_16x16x32_bf16 v[132:135], v[196:199], v[180:183], v[132:135]
	s_cmp_ge_u32 s63, 14
	s_cbranch_scc1 .Lg2_ff1_nb17_1
	s_add_u32 s58, s58, 0x800
	s_addc_u32 s59, s59, 0
	global_load_dwordx4 v[184:187], v160, s[58:59] offset:0
	global_load_dwordx4 v[188:191], v160, s[58:59] offset:1024
	global_load_dwordx4 v[192:195], v161, s[58:59] offset:0
	global_load_dwordx4 v[196:199], v161, s[58:59] offset:1024
.Lg2_ff1_nb17_1:
	ds_read_b128 v[164:167], v158 offset:8192
	ds_read_b128 v[168:171], v158 offset:10240
	ds_read_b128 v[172:175], v158 offset:12288
	ds_read_b128 v[176:179], v158 offset:14336
	s_waitcnt lgkmcnt(4)
	v_mfma_f32_16x16x32_bf16 v[0:3], v[200:203], v[136:139], v[0:3]
	v_mfma_f32_16x16x32_bf16 v[4:7], v[208:211], v[136:139], v[4:7]
	v_mfma_f32_16x16x32_bf16 v[8:11], v[200:203], v[140:143], v[8:11]
	v_mfma_f32_16x16x32_bf16 v[12:15], v[208:211], v[140:143], v[12:15]
	v_mfma_f32_16x16x32_bf16 v[16:19], v[200:203], v[144:147], v[16:19]
	v_mfma_f32_16x16x32_bf16 v[20:23], v[208:211], v[144:147], v[20:23]
	v_mfma_f32_16x16x32_bf16 v[24:27], v[200:203], v[148:151], v[24:27]
	v_mfma_f32_16x16x32_bf16 v[28:31], v[208:211], v[148:151], v[28:31]
	ds_read_b128 v[136:139], v158 offset:16384
	ds_read_b128 v[140:143], v158 offset:18432
	ds_read_b128 v[144:147], v158 offset:20480
	ds_read_b128 v[148:151], v158 offset:22528
	s_waitcnt lgkmcnt(4)
	v_mfma_f32_16x16x32_bf16 v[32:35], v[200:203], v[164:167], v[32:35]
	v_mfma_f32_16x16x32_bf16 v[36:39], v[208:211], v[164:167], v[36:39]
	v_mfma_f32_16x16x32_bf16 v[40:43], v[200:203], v[168:171], v[40:43]
	v_mfma_f32_16x16x32_bf16 v[44:47], v[208:211], v[168:171], v[44:47]
	v_mfma_f32_16x16x32_bf16 v[48:51], v[200:203], v[172:175], v[48:51]
	v_mfma_f32_16x16x32_bf16 v[52:55], v[208:211], v[172:175], v[52:55]
	v_mfma_f32_16x16x32_bf16 v[56:59], v[200:203], v[176:179], v[56:59]
	v_mfma_f32_16x16x32_bf16 v[60:63], v[208:211], v[176:179], v[60:63]
	ds_read_b128 v[164:167], v158 offset:24576
	ds_read_b128 v[168:171], v158 offset:26624
	ds_read_b128 v[172:175], v158 offset:28672
	ds_read_b128 v[176:179], v158 offset:30720
	ds_read_b128 v[180:183], v158 offset:32768
	s_waitcnt lgkmcnt(5)
	v_mfma_f32_16x16x32_bf16 v[64:67], v[200:203], v[136:139], v[64:67]
	v_mfma_f32_16x16x32_bf16 v[68:71], v[208:211], v[136:139], v[68:71]
	v_mfma_f32_16x16x32_bf16 v[72:75], v[200:203], v[140:143], v[72:75]
	v_mfma_f32_16x16x32_bf16 v[76:79], v[208:211], v[140:143], v[76:79]
	v_mfma_f32_16x16x32_bf16 v[80:83], v[200:203], v[144:147], v[80:83]
	v_mfma_f32_16x16x32_bf16 v[84:87], v[208:211], v[144:147], v[84:87]
	v_mfma_f32_16x16x32_bf16 v[88:91], v[200:203], v[148:151], v[88:91]
	v_mfma_f32_16x16x32_bf16 v[92:95], v[208:211], v[148:151], v[92:95]
	ds_read_b128 v[136:139], v159 offset:0
	ds_read_b128 v[140:143], v159 offset:2048
	ds_read_b128 v[144:147], v159 offset:4096
	ds_read_b128 v[148:151], v159 offset:6144
	s_waitcnt lgkmcnt(4)
	v_mfma_f32_16x16x32_bf16 v[96:99], v[200:203], v[164:167], v[96:99]
	v_mfma_f32_16x16x32_bf16 v[100:103], v[208:211], v[164:167], v[100:103]
	v_mfma_f32_16x16x32_bf16 v[104:107], v[200:203], v[168:171], v[104:107]
	v_mfma_f32_16x16x32_bf16 v[108:111], v[208:211], v[168:171], v[108:111]
	v_mfma_f32_16x16x32_bf16 v[112:115], v[200:203], v[172:175], v[112:115]
	v_mfma_f32_16x16x32_bf16 v[116:119], v[208:211], v[172:175], v[116:119]
	v_mfma_f32_16x16x32_bf16 v[120:123], v[200:203], v[176:179], v[120:123]
	v_mfma_f32_16x16x32_bf16 v[124:127], v[208:211], v[176:179], v[124:127]
	v_mfma_f32_16x16x32_bf16 v[128:131], v[200:203], v[180:183], v[128:131]
	v_mfma_f32_16x16x32_bf16 v[132:135], v[208:211], v[180:183], v[132:135]
	ds_read_b128 v[164:167], v159 offset:8192
	ds_read_b128 v[168:171], v159 offset:10240
	ds_read_b128 v[172:175], v159 offset:12288
	ds_read_b128 v[176:179], v159 offset:14336
	s_waitcnt lgkmcnt(4)
	v_mfma_f32_16x16x32_bf16 v[0:3], v[204:207], v[136:139], v[0:3]
	v_mfma_f32_16x16x32_bf16 v[4:7], v[240:243], v[136:139], v[4:7]
	v_mfma_f32_16x16x32_bf16 v[8:11], v[204:207], v[140:143], v[8:11]
	v_mfma_f32_16x16x32_bf16 v[12:15], v[240:243], v[140:143], v[12:15]
	v_mfma_f32_16x16x32_bf16 v[16:19], v[204:207], v[144:147], v[16:19]
	v_mfma_f32_16x16x32_bf16 v[20:23], v[240:243], v[144:147], v[20:23]
	v_mfma_f32_16x16x32_bf16 v[24:27], v[204:207], v[148:151], v[24:27]
	v_mfma_f32_16x16x32_bf16 v[28:31], v[240:243], v[148:151], v[28:31]
	ds_read_b128 v[136:139], v159 offset:16384
	ds_read_b128 v[140:143], v159 offset:18432
	ds_read_b128 v[144:147], v159 offset:20480
	ds_read_b128 v[148:151], v159 offset:22528
	s_waitcnt lgkmcnt(4)
	v_mfma_f32_16x16x32_bf16 v[32:35], v[204:207], v[164:167], v[32:35]
	v_mfma_f32_16x16x32_bf16 v[36:39], v[240:243], v[164:167], v[36:39]
	v_mfma_f32_16x16x32_bf16 v[40:43], v[204:207], v[168:171], v[40:43]
	v_mfma_f32_16x16x32_bf16 v[44:47], v[240:243], v[168:171], v[44:47]
	v_mfma_f32_16x16x32_bf16 v[48:51], v[204:207], v[172:175], v[48:51]
	v_mfma_f32_16x16x32_bf16 v[52:55], v[240:243], v[172:175], v[52:55]
	v_mfma_f32_16x16x32_bf16 v[56:59], v[204:207], v[176:179], v[56:59]
	v_mfma_f32_16x16x32_bf16 v[60:63], v[240:243], v[176:179], v[60:63]
	ds_read_b128 v[164:167], v159 offset:24576
	ds_read_b128 v[168:171], v159 offset:26624
	ds_read_b128 v[172:175], v159 offset:28672
	ds_read_b128 v[176:179], v159 offset:30720
	ds_read_b128 v[180:183], v159 offset:32768
	s_waitcnt lgkmcnt(5)
	v_mfma_f32_16x16x32_bf16 v[64:67], v[204:207], v[136:139], v[64:67]
	v_mfma_f32_16x16x32_bf16 v[68:71], v[240:243], v[136:139], v[68:71]
	v_mfma_f32_16x16x32_bf16 v[72:75], v[204:207], v[140:143], v[72:75]
	v_mfma_f32_16x16x32_bf16 v[76:79], v[240:243], v[140:143], v[76:79]
	v_mfma_f32_16x16x32_bf16 v[80:83], v[204:207], v[144:147], v[80:83]
	v_mfma_f32_16x16x32_bf16 v[84:87], v[240:243], v[144:147], v[84:87]
	v_mfma_f32_16x16x32_bf16 v[88:91], v[204:207], v[148:151], v[88:91]
	v_mfma_f32_16x16x32_bf16 v[92:95], v[240:243], v[148:151], v[92:95]
	s_waitcnt vmcnt(0) lgkmcnt(0)
	s_barrier
	s_cmp_ge_u32 s63, 14
	s_cbranch_scc1 .Lg2_ff1_nd17_1
	ds_read_b128 v[136:139], v156 offset:0
	ds_read_b128 v[140:143], v156 offset:2048
	ds_read_b128 v[144:147], v156 offset:4096
	ds_read_b128 v[148:151], v156 offset:6144
	s_add_u32 s56, s56, 0x80
	s_addc_u32 s57, s57, 0
	s_add_u32 m0, s62, 0x8800
	s_add_u32 s4, s56, 0x0
	s_addc_u32 s5, s57, 0
	global_load_lds_dwordx4 v162, s[4:5]
	s_add_u32 m0, s62, 0x9800
	s_add_u32 s4, s56, 0x10000
	s_addc_u32 s5, s57, 0
	global_load_lds_dwordx4 v162, s[4:5]
	s_add_u32 m0, s62, 0xa800
	s_add_u32 s4, s56, 0x20000
	s_addc_u32 s5, s57, 0
	global_load_lds_dwordx4 v162, s[4:5]
	s_add_u32 m0, s62, 0xb800
	s_add_u32 s4, s56, 0x30000
	s_addc_u32 s5, s57, 0
	global_load_lds_dwordx4 v162, s[4:5]
	s_add_u32 m0, s62, 0xc800
	s_add_u32 s4, s56, 0x40000
	s_addc_u32 s5, s57, 0
	global_load_lds_dwordx4 v162, s[4:5]
	s_add_u32 m0, s62, 0xd800
	s_add_u32 s4, s56, 0x50000
	s_addc_u32 s5, s57, 0
	global_load_lds_dwordx4 v162, s[4:5]
	s_add_u32 m0, s62, 0xe800
	s_add_u32 s4, s56, 0x60000
	s_addc_u32 s5, s57, 0
	global_load_lds_dwordx4 v162, s[4:5]
	s_add_u32 m0, s62, 0xf800
	s_add_u32 s4, s56, 0x70000
	s_addc_u32 s5, s57, 0
	global_load_lds_dwordx4 v162, s[4:5]
	s_cmp_gt_u32 s70, 1
	s_cbranch_scc1 .Lg2_ff1_nodma_3
	s_add_u32 m0, s62, 0x10800
	s_add_u32 s4, s56, 0x80000
	s_addc_u32 s5, s57, 0
	global_load_lds_dwordx4 v162, s[4:5]
.Lg2_ff1_nodma_3:
.Lg2_ff1_nd17_1:
	v_mfma_f32_16x16x32_bf16 v[96:99], v[204:207], v[164:167], v[96:99]
	v_mfma_f32_16x16x32_bf16 v[100:103], v[240:243], v[164:167], v[100:103]
	v_mfma_f32_16x16x32_bf16 v[104:107], v[204:207], v[168:171], v[104:107]
	v_mfma_f32_16x16x32_bf16 v[108:111], v[240:243], v[168:171], v[108:111]
	v_mfma_f32_16x16x32_bf16 v[112:115], v[204:207], v[172:175], v[112:115]
	v_mfma_f32_16x16x32_bf16 v[116:119], v[240:243], v[172:175], v[116:119]
	v_mfma_f32_16x16x32_bf16 v[120:123], v[204:207], v[176:179], v[120:123]
	v_mfma_f32_16x16x32_bf16 v[124:127], v[240:243], v[176:179], v[124:127]
	v_mfma_f32_16x16x32_bf16 v[128:131], v[204:207], v[180:183], v[128:131]
	v_mfma_f32_16x16x32_bf16 v[132:135], v[240:243], v[180:183], v[132:135]
	s_add_i32 s63, s63, 2
	s_cmp_lt_u32 s63, 16
	s_cbranch_scc1 .Lg2_ff1_loop17
	s_branch .Lg2_ff1_episel

.Lg2_ff1_loop16:
	s_add_u32 s58, s58, 0x800
	s_addc_u32 s59, s59, 0
	global_load_dwordx4 v[200:203], v160, s[58:59] offset:0
	global_load_dwordx4 v[204:207], v160, s[58:59] offset:1024
	global_load_dwordx4 v[208:211], v161, s[58:59] offset:0
	global_load_dwordx4 v[240:243], v161, s[58:59] offset:1024
	ds_read_b128 v[164:167], v156 offset:8192
	ds_read_b128 v[168:171], v156 offset:10240
	ds_read_b128 v[172:175], v156 offset:12288
	ds_read_b128 v[176:179], v156 offset:14336
	s_waitcnt lgkmcnt(4)
	v_mfma_f32_16x16x32_bf16 v[0:3], v[184:187], v[136:139], v[0:3]
	v_mfma_f32_16x16x32_bf16 v[4:7], v[192:195], v[136:139], v[4:7]
	v_mfma_f32_16x16x32_bf16 v[8:11], v[184:187], v[140:143], v[8:11]
	v_mfma_f32_16x16x32_bf16 v[12:15], v[192:195], v[140:143], v[12:15]
	v_mfma_f32_16x16x32_bf16 v[16:19], v[184:187], v[144:147], v[16:19]
	v_mfma_f32_16x16x32_bf16 v[20:23], v[192:195], v[144:147], v[20:23]
	v_mfma_f32_16x16x32_bf16 v[24:27], v[184:187], v[148:151], v[24:27]
	v_mfma_f32_16x16x32_bf16 v[28:31], v[192:195], v[148:151], v[28:31]
	ds_read_b128 v[136:139], v156 offset:16384
	ds_read_b128 v[140:143], v156 offset:18432
	ds_read_b128 v[144:147], v156 offset:20480
	ds_read_b128 v[148:151], v156 offset:22528
	s_waitcnt lgkmcnt(4)
	v_mfma_f32_16x16x32_bf16 v[32:35], v[184:187], v[164:167], v[32:35]
	v_mfma_f32_16x16x32_bf16 v[36:39], v[192:195], v[164:167], v[36:39]
	v_mfma_f32_16x16x32_bf16 v[40:43], v[184:187], v[168:171], v[40:43]
	v_mfma_f32_16x16x32_bf16 v[44:47], v[192:195], v[168:171], v[44:47]
	v_mfma_f32_16x16x32_bf16 v[48:51], v[184:187], v[172:175], v[48:51]
	v_mfma_f32_16x16x32_bf16 v[52:55], v[192:195], v[172:175], v[52:55]
	v_mfma_f32_16x16x32_bf16 v[56:59], v[184:187], v[176:179], v[56:59]
	v_mfma_f32_16x16x32_bf16 v[60:63], v[192:195], v[176:179], v[60:63]
	ds_read_b128 v[164:167], v156 offset:24576
	ds_read_b128 v[168:171], v156 offset:26624
	ds_read_b128 v[172:175], v156 offset:28672
	ds_read_b128 v[176:179], v156 offset:30720
	s_waitcnt lgkmcnt(4)
	v_mfma_f32_16x16x32_bf16 v[64:67], v[184:187], v[136:139], v[64:67]
	v_mfma_f32_16x16x32_bf16 v[68:71], v[192:195], v[136:139], v[68:71]
	v_mfma_f32_16x16x32_bf16 v[72:75], v[184:187], v[140:143], v[72:75]
	v_mfma_f32_16x16x32_bf16 v[76:79], v[192:195], v[140:143], v[76:79]
	v_mfma_f32_16x16x32_bf16 v[80:83], v[184:187], v[144:147], v[80:83]
	v_mfma_f32_16x16x32_bf16 v[84:87], v[192:195], v[144:147], v[84:87]
	v_mfma_f32_16x16x32_bf16 v[88:91], v[184:187], v[148:151], v[88:91]
	v_mfma_f32_16x16x32_bf16 v[92:95], v[192:195], v[148:151], v[92:95]
	ds_read_b128 v[136:139], v157 offset:0
	ds_read_b128 v[140:143], v157 offset:2048
	ds_read_b128 v[144:147], v157 offset:4096
	ds_read_b128 v[148:151], v157 offset:6144
	s_waitcnt lgkmcnt(4)
	v_mfma_f32_16x16x32_bf16 v[96:99], v[184:187], v[164:167], v[96:99]
	v_mfma_f32_16x16x32_bf16 v[100:103], v[192:195], v[164:167], v[100:103]
	v_mfma_f32_16x16x32_bf16 v[104:107], v[184:187], v[168:171], v[104:107]
	v_mfma_f32_16x16x32_bf16 v[108:111], v[192:195], v[168:171], v[108:111]
	v_mfma_f32_16x16x32_bf16 v[112:115], v[184:187], v[172:175], v[112:115]
	v_mfma_f32_16x16x32_bf16 v[116:119], v[192:195], v[172:175], v[116:119]
	v_mfma_f32_16x16x32_bf16 v[120:123], v[184:187], v[176:179], v[120:123]
	v_mfma_f32_16x16x32_bf16 v[124:127], v[192:195], v[176:179], v[124:127]
	ds_read_b128 v[164:167], v157 offset:8192
	ds_read_b128 v[168:171], v157 offset:10240
	ds_read_b128 v[172:175], v157 offset:12288
	ds_read_b128 v[176:179], v157 offset:14336
	s_waitcnt lgkmcnt(4)
	v_mfma_f32_16x16x32_bf16 v[0:3], v[188:191], v[136:139], v[0:3]
	v_mfma_f32_16x16x32_bf16 v[4:7], v[196:199], v[136:139], v[4:7]
	v_mfma_f32_16x16x32_bf16 v[8:11], v[188:191], v[140:143], v[8:11]
	v_mfma_f32_16x16x32_bf16 v[12:15], v[196:199], v[140:143], v[12:15]
	v_mfma_f32_16x16x32_bf16 v[16:19], v[188:191], v[144:147], v[16:19]
	v_mfma_f32_16x16x32_bf16 v[20:23], v[196:199], v[144:147], v[20:23]
	v_mfma_f32_16x16x32_bf16 v[24:27], v[188:191], v[148:151], v[24:27]
	v_mfma_f32_16x16x32_bf16 v[28:31], v[196:199], v[148:151], v[28:31]
	ds_read_b128 v[136:139], v157 offset:16384
	ds_read_b128 v[140:143], v157 offset:18432
	ds_read_b128 v[144:147], v157 offset:20480
	ds_read_b128 v[148:151], v157 offset:22528
	s_waitcnt lgkmcnt(4)
	v_mfma_f32_16x16x32_bf16 v[32:35], v[188:191], v[164:167], v[32:35]
	v_mfma_f32_16x16x32_bf16 v[36:39], v[196:199], v[164:167], v[36:39]
	v_mfma_f32_16x16x32_bf16 v[40:43], v[188:191], v[168:171], v[40:43]
	v_mfma_f32_16x16x32_bf16 v[44:47], v[196:199], v[168:171], v[44:47]
	v_mfma_f32_16x16x32_bf16 v[48:51], v[188:191], v[172:175], v[48:51]
	v_mfma_f32_16x16x32_bf16 v[52:55], v[196:199], v[172:175], v[52:55]
	v_mfma_f32_16x16x32_bf16 v[56:59], v[188:191], v[176:179], v[56:59]
	v_mfma_f32_16x16x32_bf16 v[60:63], v[196:199], v[176:179], v[60:63]
	ds_read_b128 v[164:167], v157 offset:24576
	ds_read_b128 v[168:171], v157 offset:26624
	ds_read_b128 v[172:175], v157 offset:28672
	ds_read_b128 v[176:179], v157 offset:30720
	s_waitcnt lgkmcnt(4)
	v_mfma_f32_16x16x32_bf16 v[64:67], v[188:191], v[136:139], v[64:67]
	v_mfma_f32_16x16x32_bf16 v[68:71], v[196:199], v[136:139], v[68:71]
	v_mfma_f32_16x16x32_bf16 v[72:75], v[188:191], v[140:143], v[72:75]
	v_mfma_f32_16x16x32_bf16 v[76:79], v[196:199], v[140:143], v[76:79]
	v_mfma_f32_16x16x32_bf16 v[80:83], v[188:191], v[144:147], v[80:83]
	v_mfma_f32_16x16x32_bf16 v[84:87], v[196:199], v[144:147], v[84:87]
	v_mfma_f32_16x16x32_bf16 v[88:91], v[188:191], v[148:151], v[88:91]
	v_mfma_f32_16x16x32_bf16 v[92:95], v[196:199], v[148:151], v[92:95]
	s_waitcnt vmcnt(0) lgkmcnt(0)
	s_barrier
	ds_read_b128 v[136:139], v158 offset:0
	ds_read_b128 v[140:143], v158 offset:2048
	ds_read_b128 v[144:147], v158 offset:4096
	ds_read_b128 v[148:151], v158 offset:6144
	s_cmp_ge_u32 s63, 14
	s_cbranch_scc1 .Lg2_ff1_nd16_0
	s_add_u32 s56, s56, 0x80
	s_addc_u32 s57, s57, 0
	s_add_u32 m0, s62, 0x0
	s_add_u32 s4, s56, 0x0
	s_addc_u32 s5, s57, 0
	global_load_lds_dwordx4 v162, s[4:5]
	s_add_u32 m0, s62, 0x1000
	s_add_u32 s4, s56, 0x10000
	s_addc_u32 s5, s57, 0
	global_load_lds_dwordx4 v162, s[4:5]
	s_add_u32 m0, s62, 0x2000
	s_add_u32 s4, s56, 0x20000
	s_addc_u32 s5, s57, 0
	global_load_lds_dwordx4 v162, s[4:5]
	s_add_u32 m0, s62, 0x3000
	s_add_u32 s4, s56, 0x30000
	s_addc_u32 s5, s57, 0
	global_load_lds_dwordx4 v162, s[4:5]
	s_add_u32 m0, s62, 0x4000
	s_add_u32 s4, s56, 0x40000
	s_addc_u32 s5, s57, 0
	global_load_lds_dwordx4 v162, s[4:5]
	s_add_u32 m0, s62, 0x5000
	s_add_u32 s4, s56, 0x50000
	s_addc_u32 s5, s57, 0
	global_load_lds_dwordx4 v162, s[4:5]
	s_add_u32 m0, s62, 0x6000
	s_add_u32 s4, s56, 0x60000
	s_addc_u32 s5, s57, 0
	global_load_lds_dwordx4 v162, s[4:5]
	s_add_u32 m0, s62, 0x7000
	s_add_u32 s4, s56, 0x70000
	s_addc_u32 s5, s57, 0
	global_load_lds_dwordx4 v162, s[4:5]
.Lg2_ff1_nd16_0:
	v_mfma_f32_16x16x32_bf16 v[96:99], v[188:191], v[164:167], v[96:99]
	v_mfma_f32_16x16x32_bf16 v[100:103], v[196:199], v[164:167], v[100:103]
	v_mfma_f32_16x16x32_bf16 v[104:107], v[188:191], v[168:171], v[104:107]
	v_mfma_f32_16x16x32_bf16 v[108:111], v[196:199], v[168:171], v[108:111]
	v_mfma_f32_16x16x32_bf16 v[112:115], v[188:191], v[172:175], v[112:115]
	v_mfma_f32_16x16x32_bf16 v[116:119], v[196:199], v[172:175], v[116:119]
	v_mfma_f32_16x16x32_bf16 v[120:123], v[188:191], v[176:179], v[120:123]
	v_mfma_f32_16x16x32_bf16 v[124:127], v[196:199], v[176:179], v[124:127]
	s_cmp_ge_u32 s63, 14
	s_cbranch_scc1 .Lg2_ff1_nb16_1
	s_add_u32 s58, s58, 0x800
	s_addc_u32 s59, s59, 0
	global_load_dwordx4 v[184:187], v160, s[58:59] offset:0
	global_load_dwordx4 v[188:191], v160, s[58:59] offset:1024
	global_load_dwordx4 v[192:195], v161, s[58:59] offset:0
	global_load_dwordx4 v[196:199], v161, s[58:59] offset:1024
.Lg2_ff1_nb16_1:
	ds_read_b128 v[164:167], v158 offset:8192
	ds_read_b128 v[168:171], v158 offset:10240
	ds_read_b128 v[172:175], v158 offset:12288
	ds_read_b128 v[176:179], v158 offset:14336
	s_waitcnt lgkmcnt(4)
	v_mfma_f32_16x16x32_bf16 v[0:3], v[200:203], v[136:139], v[0:3]
	v_mfma_f32_16x16x32_bf16 v[4:7], v[208:211], v[136:139], v[4:7]
	v_mfma_f32_16x16x32_bf16 v[8:11], v[200:203], v[140:143], v[8:11]
	v_mfma_f32_16x16x32_bf16 v[12:15], v[208:211], v[140:143], v[12:15]
	v_mfma_f32_16x16x32_bf16 v[16:19], v[200:203], v[144:147], v[16:19]
	v_mfma_f32_16x16x32_bf16 v[20:23], v[208:211], v[144:147], v[20:23]
	v_mfma_f32_16x16x32_bf16 v[24:27], v[200:203], v[148:151], v[24:27]
	v_mfma_f32_16x16x32_bf16 v[28:31], v[208:211], v[148:151], v[28:31]
	ds_read_b128 v[136:139], v158 offset:16384
	ds_read_b128 v[140:143], v158 offset:18432
	ds_read_b128 v[144:147], v158 offset:20480
	ds_read_b128 v[148:151], v158 offset:22528
	s_waitcnt lgkmcnt(4)
	v_mfma_f32_16x16x32_bf16 v[32:35], v[200:203], v[164:167], v[32:35]
	v_mfma_f32_16x16x32_bf16 v[36:39], v[208:211], v[164:167], v[36:39]
	v_mfma_f32_16x16x32_bf16 v[40:43], v[200:203], v[168:171], v[40:43]
	v_mfma_f32_16x16x32_bf16 v[44:47], v[208:211], v[168:171], v[44:47]
	v_mfma_f32_16x16x32_bf16 v[48:51], v[200:203], v[172:175], v[48:51]
	v_mfma_f32_16x16x32_bf16 v[52:55], v[208:211], v[172:175], v[52:55]
	v_mfma_f32_16x16x32_bf16 v[56:59], v[200:203], v[176:179], v[56:59]
	v_mfma_f32_16x16x32_bf16 v[60:63], v[208:211], v[176:179], v[60:63]
	ds_read_b128 v[164:167], v158 offset:24576
	ds_read_b128 v[168:171], v158 offset:26624
	ds_read_b128 v[172:175], v158 offset:28672
	ds_read_b128 v[176:179], v158 offset:30720
	s_waitcnt lgkmcnt(4)
	v_mfma_f32_16x16x32_bf16 v[64:67], v[200:203], v[136:139], v[64:67]
	v_mfma_f32_16x16x32_bf16 v[68:71], v[208:211], v[136:139], v[68:71]
	v_mfma_f32_16x16x32_bf16 v[72:75], v[200:203], v[140:143], v[72:75]
	v_mfma_f32_16x16x32_bf16 v[76:79], v[208:211], v[140:143], v[76:79]
	v_mfma_f32_16x16x32_bf16 v[80:83], v[200:203], v[144:147], v[80:83]
	v_mfma_f32_16x16x32_bf16 v[84:87], v[208:211], v[144:147], v[84:87]
	v_mfma_f32_16x16x32_bf16 v[88:91], v[200:203], v[148:151], v[88:91]
	v_mfma_f32_16x16x32_bf16 v[92:95], v[208:211], v[148:151], v[92:95]
	ds_read_b128 v[136:139], v159 offset:0
	ds_read_b128 v[140:143], v159 offset:2048
	ds_read_b128 v[144:147], v159 offset:4096
	ds_read_b128 v[148:151], v159 offset:6144
	s_waitcnt lgkmcnt(4)
	v_mfma_f32_16x16x32_bf16 v[96:99], v[200:203], v[164:167], v[96:99]
	v_mfma_f32_16x16x32_bf16 v[100:103], v[208:211], v[164:167], v[100:103]
	v_mfma_f32_16x16x32_bf16 v[104:107], v[200:203], v[168:171], v[104:107]
	v_mfma_f32_16x16x32_bf16 v[108:111], v[208:211], v[168:171], v[108:111]
	v_mfma_f32_16x16x32_bf16 v[112:115], v[200:203], v[172:175], v[112:115]
	v_mfma_f32_16x16x32_bf16 v[116:119], v[208:211], v[172:175], v[116:119]
	v_mfma_f32_16x16x32_bf16 v[120:123], v[200:203], v[176:179], v[120:123]
	v_mfma_f32_16x16x32_bf16 v[124:127], v[208:211], v[176:179], v[124:127]
	ds_read_b128 v[164:167], v159 offset:8192
	ds_read_b128 v[168:171], v159 offset:10240
	ds_read_b128 v[172:175], v159 offset:12288
	ds_read_b128 v[176:179], v159 offset:14336
	s_waitcnt lgkmcnt(4)
	v_mfma_f32_16x16x32_bf16 v[0:3], v[204:207], v[136:139], v[0:3]
	v_mfma_f32_16x16x32_bf16 v[4:7], v[240:243], v[136:139], v[4:7]
	v_mfma_f32_16x16x32_bf16 v[8:11], v[204:207], v[140:143], v[8:11]
	v_mfma_f32_16x16x32_bf16 v[12:15], v[240:243], v[140:143], v[12:15]
	v_mfma_f32_16x16x32_bf16 v[16:19], v[204:207], v[144:147], v[16:19]
	v_mfma_f32_16x16x32_bf16 v[20:23], v[240:243], v[144:147], v[20:23]
	v_mfma_f32_16x16x32_bf16 v[24:27], v[204:207], v[148:151], v[24:27]
	v_mfma_f32_16x16x32_bf16 v[28:31], v[240:243], v[148:151], v[28:31]
	ds_read_b128 v[136:139], v159 offset:16384
	ds_read_b128 v[140:143], v159 offset:18432
	ds_read_b128 v[144:147], v159 offset:20480
	ds_read_b128 v[148:151], v159 offset:22528
	s_waitcnt lgkmcnt(4)
	v_mfma_f32_16x16x32_bf16 v[32:35], v[204:207], v[164:167], v[32:35]
	v_mfma_f32_16x16x32_bf16 v[36:39], v[240:243], v[164:167], v[36:39]
	v_mfma_f32_16x16x32_bf16 v[40:43], v[204:207], v[168:171], v[40:43]
	v_mfma_f32_16x16x32_bf16 v[44:47], v[240:243], v[168:171], v[44:47]
	v_mfma_f32_16x16x32_bf16 v[48:51], v[204:207], v[172:175], v[48:51]
	v_mfma_f32_16x16x32_bf16 v[52:55], v[240:243], v[172:175], v[52:55]
	v_mfma_f32_16x16x32_bf16 v[56:59], v[204:207], v[176:179], v[56:59]
	v_mfma_f32_16x16x32_bf16 v[60:63], v[240:243], v[176:179], v[60:63]
	ds_read_b128 v[164:167], v159 offset:24576
	ds_read_b128 v[168:171], v159 offset:26624
	ds_read_b128 v[172:175], v159 offset:28672
	ds_read_b128 v[176:179], v159 offset:30720
	s_waitcnt lgkmcnt(4)
	v_mfma_f32_16x16x32_bf16 v[64:67], v[204:207], v[136:139], v[64:67]
	v_mfma_f32_16x16x32_bf16 v[68:71], v[240:243], v[136:139], v[68:71]
	v_mfma_f32_16x16x32_bf16 v[72:75], v[204:207], v[140:143], v[72:75]
	v_mfma_f32_16x16x32_bf16 v[76:79], v[240:243], v[140:143], v[76:79]
	v_mfma_f32_16x16x32_bf16 v[80:83], v[204:207], v[144:147], v[80:83]
	v_mfma_f32_16x16x32_bf16 v[84:87], v[240:243], v[144:147], v[84:87]
	v_mfma_f32_16x16x32_bf16 v[88:91], v[204:207], v[148:151], v[88:91]
	v_mfma_f32_16x16x32_bf16 v[92:95], v[240:243], v[148:151], v[92:95]
	s_waitcnt vmcnt(0) lgkmcnt(0)
	s_barrier
	s_cmp_ge_u32 s63, 14
	s_cbranch_scc1 .Lg2_ff1_nd16_1
	ds_read_b128 v[136:139], v156 offset:0
	ds_read_b128 v[140:143], v156 offset:2048
	ds_read_b128 v[144:147], v156 offset:4096
	ds_read_b128 v[148:151], v156 offset:6144
	s_add_u32 s56, s56, 0x80
	s_addc_u32 s57, s57, 0
	s_add_u32 m0, s62, 0x8800
	s_add_u32 s4, s56, 0x0
	s_addc_u32 s5, s57, 0
	global_load_lds_dwordx4 v162, s[4:5]
	s_add_u32 m0, s62, 0x9800
	s_add_u32 s4, s56, 0x10000
	s_addc_u32 s5, s57, 0
	global_load_lds_dwordx4 v162, s[4:5]
	s_add_u32 m0, s62, 0xa800
	s_add_u32 s4, s56, 0x20000
	s_addc_u32 s5, s57, 0
	global_load_lds_dwordx4 v162, s[4:5]
	s_add_u32 m0, s62, 0xb800
	s_add_u32 s4, s56, 0x30000
	s_addc_u32 s5, s57, 0
	global_load_lds_dwordx4 v162, s[4:5]
	s_add_u32 m0, s62, 0xc800
	s_add_u32 s4, s56, 0x40000
	s_addc_u32 s5, s57, 0
	global_load_lds_dwordx4 v162, s[4:5]
	s_add_u32 m0, s62, 0xd800
	s_add_u32 s4, s56, 0x50000
	s_addc_u32 s5, s57, 0
	global_load_lds_dwordx4 v162, s[4:5]
	s_add_u32 m0, s62, 0xe800
	s_add_u32 s4, s56, 0x60000
	s_addc_u32 s5, s57, 0
	global_load_lds_dwordx4 v162, s[4:5]
	s_add_u32 m0, s62, 0xf800
	s_add_u32 s4, s56, 0x70000
	s_addc_u32 s5, s57, 0
	global_load_lds_dwordx4 v162, s[4:5]

.Lg2_up_loop17:
	s_add_u32 s58, s58, 0x800
	s_addc_u32 s59, s59, 0
	global_load_dwordx4 v[200:203], v160, s[58:59] offset:0
	global_load_dwordx4 v[204:207], v160, s[58:59] offset:1024
	global_load_dwordx4 v[208:211], v161, s[58:59] offset:0
	global_load_dwordx4 v[240:243], v161, s[58:59] offset:1024
	ds_read_b128 v[164:167], v156 offset:8192
	ds_read_b128 v[168:171], v156 offset:10240
	ds_read_b128 v[172:175], v156 offset:12288
	ds_read_b128 v[176:179], v156 offset:14336
	s_waitcnt lgkmcnt(4)
	v_mfma_f32_16x16x32_bf16 v[0:3], v[184:187], v[136:139], v[0:3]
	v_mfma_f32_16x16x32_bf16 v[4:7], v[192:195], v[136:139], v[4:7]
	v_mfma_f32_16x16x32_bf16 v[8:11], v[184:187], v[140:143], v[8:11]
	v_mfma_f32_16x16x32_bf16 v[12:15], v[192:195], v[140:143], v[12:15]
	v_mfma_f32_16x16x32_bf16 v[16:19], v[184:187], v[144:147], v[16:19]
	v_mfma_f32_16x16x32_bf16 v[20:23], v[192:195], v[144:147], v[20:23]
	v_mfma_f32_16x16x32_bf16 v[24:27], v[184:187], v[148:151], v[24:27]
	v_mfma_f32_16x16x32_bf16 v[28:31], v[192:195], v[148:151], v[28:31]
	ds_read_b128 v[136:139], v156 offset:16384
	ds_read_b128 v[140:143], v156 offset:18432
	ds_read_b128 v[144:147], v156 offset:20480
	ds_read_b128 v[148:151], v156 offset:22528
	s_waitcnt lgkmcnt(4)
	v_mfma_f32_16x16x32_bf16 v[32:35], v[184:187], v[164:167], v[32:35]
	v_mfma_f32_16x16x32_bf16 v[36:39], v[192:195], v[164:167], v[36:39]
	v_mfma_f32_16x16x32_bf16 v[40:43], v[184:187], v[168:171], v[40:43]
	v_mfma_f32_16x16x32_bf16 v[44:47], v[192:195], v[168:171], v[44:47]
	v_mfma_f32_16x16x32_bf16 v[48:51], v[184:187], v[172:175], v[48:51]
	v_mfma_f32_16x16x32_bf16 v[52:55], v[192:195], v[172:175], v[52:55]
	v_mfma_f32_16x16x32_bf16 v[56:59], v[184:187], v[176:179], v[56:59]
	v_mfma_f32_16x16x32_bf16 v[60:63], v[192:195], v[176:179], v[60:63]
	ds_read_b128 v[164:167], v156 offset:24576
	ds_read_b128 v[168:171], v156 offset:26624
	ds_read_b128 v[172:175], v156 offset:28672
	ds_read_b128 v[176:179], v156 offset:30720
	ds_read_b128 v[180:183], v156 offset:32768
	s_waitcnt lgkmcnt(5)
	v_mfma_f32_16x16x32_bf16 v[64:67], v[184:187], v[136:139], v[64:67]
	v_mfma_f32_16x16x32_bf16 v[68:71], v[192:195], v[136:139], v[68:71]
	v_mfma_f32_16x16x32_bf16 v[72:75], v[184:187], v[140:143], v[72:75]
	v_mfma_f32_16x16x32_bf16 v[76:79], v[192:195], v[140:143], v[76:79]
	v_mfma_f32_16x16x32_bf16 v[80:83], v[184:187], v[144:147], v[80:83]
	v_mfma_f32_16x16x32_bf16 v[84:87], v[192:195], v[144:147], v[84:87]
	v_mfma_f32_16x16x32_bf16 v[88:91], v[184:187], v[148:151], v[88:91]
	v_mfma_f32_16x16x32_bf16 v[92:95], v[192:195], v[148:151], v[92:95]
	ds_read_b128 v[136:139], v157 offset:0
	ds_read_b128 v[140:143], v157 offset:2048
	ds_read_b128 v[144:147], v157 offset:4096
	ds_read_b128 v[148:151], v157 offset:6144
	s_waitcnt lgkmcnt(4)
	v_mfma_f32_16x16x32_bf16 v[96:99], v[184:187], v[164:167], v[96:99]
	v_mfma_f32_16x16x32_bf16 v[100:103], v[192:195], v[164:167], v[100:103]
	v_mfma_f32_16x16x32_bf16 v[104:107], v[184:187], v[168:171], v[104:107]
	v_mfma_f32_16x16x32_bf16 v[108:111], v[192:195], v[168:171], v[108:111]
	v_mfma_f32_16x16x32_bf16 v[112:115], v[184:187], v[172:175], v[112:115]
	v_mfma_f32_16x16x32_bf16 v[116:119], v[192:195], v[172:175], v[116:119]
	v_mfma_f32_16x16x32_bf16 v[120:123], v[184:187], v[176:179], v[120:123]
	v_mfma_f32_16x16x32_bf16 v[124:127], v[192:195], v[176:179], v[124:127]
	v_mfma_f32_16x16x32_bf16 v[128:131], v[184:187], v[180:183], v[128:131]
	v_mfma_f32_16x16x32_bf16 v[132:135], v[192:195], v[180:183], v[132:135]
	ds_read_b128 v[164:167], v157 offset:8192
	ds_read_b128 v[168:171], v157 offset:10240
	ds_read_b128 v[172:175], v157 offset:12288
	ds_read_b128 v[176:179], v157 offset:14336
	s_waitcnt lgkmcnt(4)
	v_mfma_f32_16x16x32_bf16 v[0:3], v[188:191], v[136:139], v[0:3]
	v_mfma_f32_16x16x32_bf16 v[4:7], v[196:199], v[136:139], v[4:7]
	v_mfma_f32_16x16x32_bf16 v[8:11], v[188:191], v[140:143], v[8:11]
	v_mfma_f32_16x16x32_bf16 v[12:15], v[196:199], v[140:143], v[12:15]
	v_mfma_f32_16x16x32_bf16 v[16:19], v[188:191], v[144:147], v[16:19]
	v_mfma_f32_16x16x32_bf16 v[20:23], v[196:199], v[144:147], v[20:23]
	v_mfma_f32_16x16x32_bf16 v[24:27], v[188:191], v[148:151], v[24:27]
	v_mfma_f32_16x16x32_bf16 v[28:31], v[196:199], v[148:151], v[28:31]
	ds_read_b128 v[136:139], v157 offset:16384
	ds_read_b128 v[140:143], v157 offset:18432
	ds_read_b128 v[144:147], v157 offset:20480
	ds_read_b128 v[148:151], v157 offset:22528
	s_waitcnt lgkmcnt(4)
	v_mfma_f32_16x16x32_bf16 v[32:35], v[188:191], v[164:167], v[32:35]
	v_mfma_f32_16x16x32_bf16 v[36:39], v[196:199], v[164:167], v[36:39]
	v_mfma_f32_16x16x32_bf16 v[40:43], v[188:191], v[168:171], v[40:43]
	v_mfma_f32_16x16x32_bf16 v[44:47], v[196:199], v[168:171], v[44:47]
	v_mfma_f32_16x16x32_bf16 v[48:51], v[188:191], v[172:175], v[48:51]
	v_mfma_f32_16x16x32_bf16 v[52:55], v[196:199], v[172:175], v[52:55]
	v_mfma_f32_16x16x32_bf16 v[56:59], v[188:191], v[176:179], v[56:59]
	v_mfma_f32_16x16x32_bf16 v[60:63], v[196:199], v[176:179], v[60:63]
	ds_read_b128 v[164:167], v157 offset:24576
	ds_read_b128 v[168:171], v157 offset:26624
	ds_read_b128 v[172:175], v157 offset:28672
	ds_read_b128 v[176:179], v157 offset:30720
	ds_read_b128 v[180:183], v157 offset:32768
	s_waitcnt lgkmcnt(5)
	v_mfma_f32_16x16x32_bf16 v[64:67], v[188:191], v[136:139], v[64:67]
	v_mfma_f32_16x16x32_bf16 v[68:71], v[196:199], v[136:139], v[68:71]
	v_mfma_f32_16x16x32_bf16 v[72:75], v[188:191], v[140:143], v[72:75]
	v_mfma_f32_16x16x32_bf16 v[76:79], v[196:199], v[140:143], v[76:79]
	v_mfma_f32_16x16x32_bf16 v[80:83], v[188:191], v[144:147], v[80:83]
	v_mfma_f32_16x16x32_bf16 v[84:87], v[196:199], v[144:147], v[84:87]
	v_mfma_f32_16x16x32_bf16 v[88:91], v[188:191], v[148:151], v[88:91]
	v_mfma_f32_16x16x32_bf16 v[92:95], v[196:199], v[148:151], v[92:95]
	s_waitcnt vmcnt(0) lgkmcnt(0)
	s_barrier
	ds_read_b128 v[136:139], v158 offset:0
	ds_read_b128 v[140:143], v158 offset:2048
	ds_read_b128 v[144:147], v158 offset:4096
	ds_read_b128 v[148:151], v158 offset:6144
	s_cmp_ge_u32 s63, 2
	s_cbranch_scc1 .Lg2_up_nd17_0
	s_add_u32 s56, s56, 0x80
	s_addc_u32 s57, s57, 0
	s_add_u32 m0, s62, 0x0
	s_add_u32 s4, s56, 0x0
	s_addc_u32 s5, s57, 0
	global_load_lds_dwordx4 v162, s[4:5]
	s_add_u32 m0, s62, 0x1000
	s_add_u32 s4, s56, 0x72000
	s_addc_u32 s5, s57, 0
	global_load_lds_dwordx4 v162, s[4:5]
	s_add_u32 m0, s62, 0x2000
	s_add_u32 s4, s56, 0xe4000
	s_addc_u32 s5, s57, 0
	global_load_lds_dwordx4 v162, s[4:5]
	s_add_u32 m0, s62, 0x3000
	s_add_u32 s4, s56, 0x156000
	s_addc_u32 s5, s57, 0
	global_load_lds_dwordx4 v162, s[4:5]
	s_add_u32 m0, s62, 0x4000
	s_add_u32 s4, s56, 0x1c8000
	s_addc_u32 s5, s57, 0
	global_load_lds_dwordx4 v162, s[4:5]
	s_add_u32 m0, s62, 0x5000
	s_add_u32 s4, s56, 0x23a000
	s_addc_u32 s5, s57, 0
	global_load_lds_dwordx4 v162, s[4:5]
	s_add_u32 m0, s62, 0x6000
	s_add_u32 s4, s56, 0x2ac000
	s_addc_u32 s5, s57, 0
	global_load_lds_dwordx4 v162, s[4:5]
	s_add_u32 m0, s62, 0x7000
	s_add_u32 s4, s56, 0x31e000
	s_addc_u32 s5, s57, 0
	global_load_lds_dwordx4 v162, s[4:5]
	s_cmp_gt_u32 s70, 1
	s_cbranch_scc1 .Lg2_up_nodma_2
	s_add_u32 m0, s62, 0x8000
	s_add_u32 s4, s56, 0x390000
	s_addc_u32 s5, s57, 0
	global_load_lds_dwordx4 v162, s[4:5]
.Lg2_up_nodma_2:
.Lg2_up_nd17_0:
	v_mfma_f32_16x16x32_bf16 v[96:99], v[188:191], v[164:167], v[96:99]
	v_mfma_f32_16x16x32_bf16 v[100:103], v[196:199], v[164:167], v[100:103]
	v_mfma_f32_16x16x32_bf16 v[104:107], v[188:191], v[168:171], v[104:107]
	v_mfma_f32_16x16x32_bf16 v[108:111], v[196:199], v[168:171], v[108:111]
	v_mfma_f32_16x16x32_bf16 v[112:115], v[188:191], v[172:175], v[112:115]
	v_mfma_f32_16x16x32_bf16 v[116:119], v[196:199], v[172:175], v[116:119]
	v_mfma_f32_16x16x32_bf16 v[120:123], v[188:191], v[176:179], v[120:123]
	v_mfma_f32_16x16x32_bf16 v[124:127], v[196:199], v[176:179], v[124:127]
	v_mfma_f32_16x16x32_bf16 v[128:131], v[188:191], v[180:183], v[128:131]
	v_mfma_f32_16x16x32_bf16 v[132:135], v[196:199], v[180:183], v[132:135]
	s_cmp_ge_u32 s63, 2
	s_cbranch_scc1 .Lg2_up_nb17_1
	s_add_u32 s58, s58, 0x800
	s_addc_u32 s59, s59, 0
	global_load_dwordx4 v[184:187], v160, s[58:59] offset:0
	global_load_dwordx4 v[188:191], v160, s[58:59] offset:1024
	global_load_dwordx4 v[192:195], v161, s[58:59] offset:0
	global_load_dwordx4 v[196:199], v161, s[58:59] offset:1024
.Lg2_up_nb17_1:
	ds_read_b128 v[164:167], v158 offset:8192
	ds_read_b128 v[168:171], v158 offset:10240
	ds_read_b128 v[172:175], v158 offset:12288
	ds_read_b128 v[176:179], v158 offset:14336
	s_waitcnt lgkmcnt(4)
	v_mfma_f32_16x16x32_bf16 v[0:3], v[200:203], v[136:139], v[0:3]
	v_mfma_f32_16x16x32_bf16 v[4:7], v[208:211], v[136:139], v[4:7]
	v_mfma_f32_16x16x32_bf16 v[8:11], v[200:203], v[140:143], v[8:11]
	v_mfma_f32_16x16x32_bf16 v[12:15], v[208:211], v[140:143], v[12:15]
	v_mfma_f32_16x16x32_bf16 v[16:19], v[200:203], v[144:147], v[16:19]
	v_mfma_f32_16x16x32_bf16 v[20:23], v[208:211], v[144:147], v[20:23]
	v_mfma_f32_16x16x32_bf16 v[24:27], v[200:203], v[148:151], v[24:27]
	v_mfma_f32_16x16x32_bf16 v[28:31], v[208:211], v[148:151], v[28:31]
	ds_read_b128 v[136:139], v158 offset:16384
	ds_read_b128 v[140:143], v158 offset:18432
	ds_read_b128 v[144:147], v158 offset:20480
	ds_read_b128 v[148:151], v158 offset:22528
	s_waitcnt lgkmcnt(4)
	v_mfma_f32_16x16x32_bf16 v[32:35], v[200:203], v[164:167], v[32:35]
	v_mfma_f32_16x16x32_bf16 v[36:39], v[208:211], v[164:167], v[36:39]
	v_mfma_f32_16x16x32_bf16 v[40:43], v[200:203], v[168:171], v[40:43]
	v_mfma_f32_16x16x32_bf16 v[44:47], v[208:211], v[168:171], v[44:47]
	v_mfma_f32_16x16x32_bf16 v[48:51], v[200:203], v[172:175], v[48:51]
	v_mfma_f32_16x16x32_bf16 v[52:55], v[208:211], v[172:175], v[52:55]
	v_mfma_f32_16x16x32_bf16 v[56:59], v[200:203], v[176:179], v[56:59]
	v_mfma_f32_16x16x32_bf16 v[60:63], v[208:211], v[176:179], v[60:63]
	ds_read_b128 v[164:167], v158 offset:24576
	ds_read_b128 v[168:171], v158 offset:26624
	ds_read_b128 v[172:175], v158 offset:28672
	ds_read_b128 v[176:179], v158 offset:30720
	ds_read_b128 v[180:183], v158 offset:32768
	s_waitcnt lgkmcnt(5)
	v_mfma_f32_16x16x32_bf16 v[64:67], v[200:203], v[136:139], v[64:67]
	v_mfma_f32_16x16x32_bf16 v[68:71], v[208:211], v[136:139], v[68:71]
	v_mfma_f32_16x16x32_bf16 v[72:75], v[200:203], v[140:143], v[72:75]
	v_mfma_f32_16x16x32_bf16 v[76:79], v[208:211], v[140:143], v[76:79]
	v_mfma_f32_16x16x32_bf16 v[80:83], v[200:203], v[144:147], v[80:83]
	v_mfma_f32_16x16x32_bf16 v[84:87], v[208:211], v[144:147], v[84:87]
	v_mfma_f32_16x16x32_bf16 v[88:91], v[200:203], v[148:151], v[88:91]
	v_mfma_f32_16x16x32_bf16 v[92:95], v[208:211], v[148:151], v[92:95]
	ds_read_b128 v[136:139], v159 offset:0
	ds_read_b128 v[140:143], v159 offset:2048
	ds_read_b128 v[144:147], v159 offset:4096
	ds_read_b128 v[148:151], v159 offset:6144
	s_waitcnt lgkmcnt(4)
	v_mfma_f32_16x16x32_bf16 v[96:99], v[200:203], v[164:167], v[96:99]
	v_mfma_f32_16x16x32_bf16 v[100:103], v[208:211], v[164:167], v[100:103]
	v_mfma_f32_16x16x32_bf16 v[104:107], v[200:203], v[168:171], v[104:107]
	v_mfma_f32_16x16x32_bf16 v[108:111], v[208:211], v[168:171], v[108:111]
	v_mfma_f32_16x16x32_bf16 v[112:115], v[200:203], v[172:175], v[112:115]
	v_mfma_f32_16x16x32_bf16 v[116:119], v[208:211], v[172:175], v[116:119]
	v_mfma_f32_16x16x32_bf16 v[120:123], v[200:203], v[176:179], v[120:123]
	v_mfma_f32_16x16x32_bf16 v[124:127], v[208:211], v[176:179], v[124:127]
	v_mfma_f32_16x16x32_bf16 v[128:131], v[200:203], v[180:183], v[128:131]
	v_mfma_f32_16x16x32_bf16 v[132:135], v[208:211], v[180:183], v[132:135]
	ds_read_b128 v[164:167], v159 offset:8192
	ds_read_b128 v[168:171], v159 offset:10240
	ds_read_b128 v[172:175], v159 offset:12288
	ds_read_b128 v[176:179], v159 offset:14336
	s_waitcnt lgkmcnt(4)
	v_mfma_f32_16x16x32_bf16 v[0:3], v[204:207], v[136:139], v[0:3]
	v_mfma_f32_16x16x32_bf16 v[4:7], v[240:243], v[136:139], v[4:7]
	v_mfma_f32_16x16x32_bf16 v[8:11], v[204:207], v[140:143], v[8:11]
	v_mfma_f32_16x16x32_bf16 v[12:15], v[240:243], v[140:143], v[12:15]
	v_mfma_f32_16x16x32_bf16 v[16:19], v[204:207], v[144:147], v[16:19]
	v_mfma_f32_16x16x32_bf16 v[20:23], v[240:243], v[144:147], v[20:23]
	v_mfma_f32_16x16x32_bf16 v[24:27], v[204:207], v[148:151], v[24:27]
	v_mfma_f32_16x16x32_bf16 v[28:31], v[240:243], v[148:151], v[28:31]
	ds_read_b128 v[136:139], v159 offset:16384
	ds_read_b128 v[140:143], v159 offset:18432
	ds_read_b128 v[144:147], v159 offset:20480
	ds_read_b128 v[148:151], v159 offset:22528
	s_waitcnt lgkmcnt(4)
	v_mfma_f32_16x16x32_bf16 v[32:35], v[204:207], v[164:167], v[32:35]
	v_mfma_f32_16x16x32_bf16 v[36:39], v[240:243], v[164:167], v[36:39]
	v_mfma_f32_16x16x32_bf16 v[40:43], v[204:207], v[168:171], v[40:43]
	v_mfma_f32_16x16x32_bf16 v[44:47], v[240:243], v[168:171], v[44:47]
	v_mfma_f32_16x16x32_bf16 v[48:51], v[204:207], v[172:175], v[48:51]
	v_mfma_f32_16x16x32_bf16 v[52:55], v[240:243], v[172:175], v[52:55]
	v_mfma_f32_16x16x32_bf16 v[56:59], v[204:207], v[176:179], v[56:59]
	v_mfma_f32_16x16x32_bf16 v[60:63], v[240:243], v[176:179], v[60:63]
	ds_read_b128 v[164:167], v159 offset:24576
	ds_read_b128 v[168:171], v159 offset:26624
	ds_read_b128 v[172:175], v159 offset:28672
	ds_read_b128 v[176:179], v159 offset:30720
	ds_read_b128 v[180:183], v159 offset:32768
	s_waitcnt lgkmcnt(5)
	v_mfma_f32_16x16x32_bf16 v[64:67], v[204:207], v[136:139], v[64:67]
	v_mfma_f32_16x16x32_bf16 v[68:71], v[240:243], v[136:139], v[68:71]
	v_mfma_f32_16x16x32_bf16 v[72:75], v[204:207], v[140:143], v[72:75]
	v_mfma_f32_16x16x32_bf16 v[76:79], v[240:243], v[140:143], v[76:79]
	v_mfma_f32_16x16x32_bf16 v[80:83], v[204:207], v[144:147], v[80:83]
	v_mfma_f32_16x16x32_bf16 v[84:87], v[240:243], v[144:147], v[84:87]
	v_mfma_f32_16x16x32_bf16 v[88:91], v[204:207], v[148:151], v[88:91]
	v_mfma_f32_16x16x32_bf16 v[92:95], v[240:243], v[148:151], v[92:95]
	s_waitcnt vmcnt(0) lgkmcnt(0)
	s_barrier
	s_cmp_ge_u32 s63, 2
	s_cbranch_scc1 .Lg2_up_nd17_1
	ds_read_b128 v[136:139], v156 offset:0
	ds_read_b128 v[140:143], v156 offset:2048
	ds_read_b128 v[144:147], v156 offset:4096
	ds_read_b128 v[148:151], v156 offset:6144
	s_add_u32 s56, s56, 0x80
	s_addc_u32 s57, s57, 0
	s_add_u32 m0, s62, 0x8800
	s_add_u32 s4, s56, 0x0
	s_addc_u32 s5, s57, 0
	global_load_lds_dwordx4 v162, s[4:5]
	s_add_u32 m0, s62, 0x9800
	s_add_u32 s4, s56, 0x72000
	s_addc_u32 s5, s57, 0
	global_load_lds_dwordx4 v162, s[4:5]
	s_add_u32 m0, s62, 0xa800
	s_add_u32 s4, s56, 0xe4000
	s_addc_u32 s5, s57, 0
	global_load_lds_dwordx4 v162, s[4:5]
	s_add_u32 m0, s62, 0xb800
	s_add_u32 s4, s56, 0x156000
	s_addc_u32 s5, s57, 0
	global_load_lds_dwordx4 v162, s[4:5]
	s_add_u32 m0, s62, 0xc800
	s_add_u32 s4, s56, 0x1c8000
	s_addc_u32 s5, s57, 0
	global_load_lds_dwordx4 v162, s[4:5]
	s_add_u32 m0, s62, 0xd800
	s_add_u32 s4, s56, 0x23a000
	s_addc_u32 s5, s57, 0
	global_load_lds_dwordx4 v162, s[4:5]
	s_add_u32 m0, s62, 0xe800
	s_add_u32 s4, s56, 0x2ac000
	s_addc_u32 s5, s57, 0
	global_load_lds_dwordx4 v162, s[4:5]
	s_add_u32 m0, s62, 0xf800
	s_add_u32 s4, s56, 0x31e000
	s_addc_u32 s5, s57, 0
	global_load_lds_dwordx4 v162, s[4:5]
	s_cmp_gt_u32 s70, 1
	s_cbranch_scc1 .Lg2_up_nodma_3
	s_add_u32 m0, s62, 0x10800
	s_add_u32 s4, s56, 0x390000
	s_addc_u32 s5, s57, 0
	global_load_lds_dwordx4 v162, s[4:5]
.Lg2_up_nodma_3:
.Lg2_up_nd17_1:
	v_mfma_f32_16x16x32_bf16 v[96:99], v[204:207], v[164:167], v[96:99]
	v_mfma_f32_16x16x32_bf16 v[100:103], v[240:243], v[164:167], v[100:103]
	v_mfma_f32_16x16x32_bf16 v[104:107], v[204:207], v[168:171], v[104:107]
	v_mfma_f32_16x16x32_bf16 v[108:111], v[240:243], v[168:171], v[108:111]
	v_mfma_f32_16x16x32_bf16 v[112:115], v[204:207], v[172:175], v[112:115]
	v_mfma_f32_16x16x32_bf16 v[116:119], v[240:243], v[172:175], v[116:119]
	v_mfma_f32_16x16x32_bf16 v[120:123], v[204:207], v[176:179], v[120:123]
	v_mfma_f32_16x16x32_bf16 v[124:127], v[240:243], v[176:179], v[124:127]
	v_mfma_f32_16x16x32_bf16 v[128:131], v[204:207], v[180:183], v[128:131]
	v_mfma_f32_16x16x32_bf16 v[132:135], v[240:243], v[180:183], v[132:135]
	s_add_i32 s63, s63, 2
	s_cmp_lt_u32 s63, 4
	s_cbranch_scc1 .Lg2_up_loop17
	s_branch .Lg2_up_episel

.Lg2_up_loop16:
	s_add_u32 s58, s58, 0x800
	s_addc_u32 s59, s59, 0
	global_load_dwordx4 v[200:203], v160, s[58:59] offset:0
	global_load_dwordx4 v[204:207], v160, s[58:59] offset:1024
	global_load_dwordx4 v[208:211], v161, s[58:59] offset:0
	global_load_dwordx4 v[240:243], v161, s[58:59] offset:1024
	ds_read_b128 v[164:167], v156 offset:8192
	ds_read_b128 v[168:171], v156 offset:10240
	ds_read_b128 v[172:175], v156 offset:12288
	ds_read_b128 v[176:179], v156 offset:14336
	s_waitcnt lgkmcnt(4)
	v_mfma_f32_16x16x32_bf16 v[0:3], v[184:187], v[136:139], v[0:3]
	v_mfma_f32_16x16x32_bf16 v[4:7], v[192:195], v[136:139], v[4:7]
	v_mfma_f32_16x16x32_bf16 v[8:11], v[184:187], v[140:143], v[8:11]
	v_mfma_f32_16x16x32_bf16 v[12:15], v[192:195], v[140:143], v[12:15]
	v_mfma_f32_16x16x32_bf16 v[16:19], v[184:187], v[144:147], v[16:19]
	v_mfma_f32_16x16x32_bf16 v[20:23], v[192:195], v[144:147], v[20:23]
	v_mfma_f32_16x16x32_bf16 v[24:27], v[184:187], v[148:151], v[24:27]
	v_mfma_f32_16x16x32_bf16 v[28:31], v[192:195], v[148:151], v[28:31]
	ds_read_b128 v[136:139], v156 offset:16384
	ds_read_b128 v[140:143], v156 offset:18432
	ds_read_b128 v[144:147], v156 offset:20480
	ds_read_b128 v[148:151], v156 offset:22528
	s_waitcnt lgkmcnt(4)
	v_mfma_f32_16x16x32_bf16 v[32:35], v[184:187], v[164:167], v[32:35]
	v_mfma_f32_16x16x32_bf16 v[36:39], v[192:195], v[164:167], v[36:39]
	v_mfma_f32_16x16x32_bf16 v[40:43], v[184:187], v[168:171], v[40:43]
	v_mfma_f32_16x16x32_bf16 v[44:47], v[192:195], v[168:171], v[44:47]
	v_mfma_f32_16x16x32_bf16 v[48:51], v[184:187], v[172:175], v[48:51]
	v_mfma_f32_16x16x32_bf16 v[52:55], v[192:195], v[172:175], v[52:55]
	v_mfma_f32_16x16x32_bf16 v[56:59], v[184:187], v[176:179], v[56:59]
	v_mfma_f32_16x16x32_bf16 v[60:63], v[192:195], v[176:179], v[60:63]
	ds_read_b128 v[164:167], v156 offset:24576
	ds_read_b128 v[168:171], v156 offset:26624
	ds_read_b128 v[172:175], v156 offset:28672
	ds_read_b128 v[176:179], v156 offset:30720
	s_waitcnt lgkmcnt(4)
	v_mfma_f32_16x16x32_bf16 v[64:67], v[184:187], v[136:139], v[64:67]
	v_mfma_f32_16x16x32_bf16 v[68:71], v[192:195], v[136:139], v[68:71]
	v_mfma_f32_16x16x32_bf16 v[72:75], v[184:187], v[140:143], v[72:75]
	v_mfma_f32_16x16x32_bf16 v[76:79], v[192:195], v[140:143], v[76:79]
	v_mfma_f32_16x16x32_bf16 v[80:83], v[184:187], v[144:147], v[80:83]
	v_mfma_f32_16x16x32_bf16 v[84:87], v[192:195], v[144:147], v[84:87]
	v_mfma_f32_16x16x32_bf16 v[88:91], v[184:187], v[148:151], v[88:91]
	v_mfma_f32_16x16x32_bf16 v[92:95], v[192:195], v[148:151], v[92:95]
	ds_read_b128 v[136:139], v157 offset:0
	ds_read_b128 v[140:143], v157 offset:2048
	ds_read_b128 v[144:147], v157 offset:4096
	ds_read_b128 v[148:151], v157 offset:6144
	s_waitcnt lgkmcnt(4)
	v_mfma_f32_16x16x32_bf16 v[96:99], v[184:187], v[164:167], v[96:99]
	v_mfma_f32_16x16x32_bf16 v[100:103], v[192:195], v[164:167], v[100:103]
	v_mfma_f32_16x16x32_bf16 v[104:107], v[184:187], v[168:171], v[104:107]
	v_mfma_f32_16x16x32_bf16 v[108:111], v[192:195], v[168:171], v[108:111]
	v_mfma_f32_16x16x32_bf16 v[112:115], v[184:187], v[172:175], v[112:115]
	v_mfma_f32_16x16x32_bf16 v[116:119], v[192:195], v[172:175], v[116:119]
	v_mfma_f32_16x16x32_bf16 v[120:123], v[184:187], v[176:179], v[120:123]
	v_mfma_f32_16x16x32_bf16 v[124:127], v[192:195], v[176:179], v[124:127]
	ds_read_b128 v[164:167], v157 offset:8192
	ds_read_b128 v[168:171], v157 offset:10240
	ds_read_b128 v[172:175], v157 offset:12288
	ds_read_b128 v[176:179], v157 offset:14336
	s_waitcnt lgkmcnt(4)
	v_mfma_f32_16x16x32_bf16 v[0:3], v[188:191], v[136:139], v[0:3]
	v_mfma_f32_16x16x32_bf16 v[4:7], v[196:199], v[136:139], v[4:7]
	v_mfma_f32_16x16x32_bf16 v[8:11], v[188:191], v[140:143], v[8:11]
	v_mfma_f32_16x16x32_bf16 v[12:15], v[196:199], v[140:143], v[12:15]
	v_mfma_f32_16x16x32_bf16 v[16:19], v[188:191], v[144:147], v[16:19]
	v_mfma_f32_16x16x32_bf16 v[20:23], v[196:199], v[144:147], v[20:23]
	v_mfma_f32_16x16x32_bf16 v[24:27], v[188:191], v[148:151], v[24:27]
	v_mfma_f32_16x16x32_bf16 v[28:31], v[196:199], v[148:151], v[28:31]
	ds_read_b128 v[136:139], v157 offset:16384
	ds_read_b128 v[140:143], v157 offset:18432
	ds_read_b128 v[144:147], v157 offset:20480
	ds_read_b128 v[148:151], v157 offset:22528
	s_waitcnt lgkmcnt(4)
	v_mfma_f32_16x16x32_bf16 v[32:35], v[188:191], v[164:167], v[32:35]
	v_mfma_f32_16x16x32_bf16 v[36:39], v[196:199], v[164:167], v[36:39]
	v_mfma_f32_16x16x32_bf16 v[40:43], v[188:191], v[168:171], v[40:43]
	v_mfma_f32_16x16x32_bf16 v[44:47], v[196:199], v[168:171], v[44:47]
	v_mfma_f32_16x16x32_bf16 v[48:51], v[188:191], v[172:175], v[48:51]
	v_mfma_f32_16x16x32_bf16 v[52:55], v[196:199], v[172:175], v[52:55]
	v_mfma_f32_16x16x32_bf16 v[56:59], v[188:191], v[176:179], v[56:59]
	v_mfma_f32_16x16x32_bf16 v[60:63], v[196:199], v[176:179], v[60:63]
	ds_read_b128 v[164:167], v157 offset:24576
	ds_read_b128 v[168:171], v157 offset:26624
	ds_read_b128 v[172:175], v157 offset:28672
	ds_read_b128 v[176:179], v157 offset:30720
	s_waitcnt lgkmcnt(4)
	v_mfma_f32_16x16x32_bf16 v[64:67], v[188:191], v[136:139], v[64:67]
	v_mfma_f32_16x16x32_bf16 v[68:71], v[196:199], v[136:139], v[68:71]
	v_mfma_f32_16x16x32_bf16 v[72:75], v[188:191], v[140:143], v[72:75]
	v_mfma_f32_16x16x32_bf16 v[76:79], v[196:199], v[140:143], v[76:79]
	v_mfma_f32_16x16x32_bf16 v[80:83], v[188:191], v[144:147], v[80:83]
	v_mfma_f32_16x16x32_bf16 v[84:87], v[196:199], v[144:147], v[84:87]
	v_mfma_f32_16x16x32_bf16 v[88:91], v[188:191], v[148:151], v[88:91]
	v_mfma_f32_16x16x32_bf16 v[92:95], v[196:199], v[148:151], v[92:95]
	s_waitcnt vmcnt(0) lgkmcnt(0)
	s_barrier
	ds_read_b128 v[136:139], v158 offset:0
	ds_read_b128 v[140:143], v158 offset:2048
	ds_read_b128 v[144:147], v158 offset:4096
	ds_read_b128 v[148:151], v158 offset:6144
	s_cmp_ge_u32 s63, 2
	s_cbranch_scc1 .Lg2_up_nd16_0
	s_add_u32 s56, s56, 0x80
	s_addc_u32 s57, s57, 0
	s_add_u32 m0, s62, 0x0
	s_add_u32 s4, s56, 0x0
	s_addc_u32 s5, s57, 0
	global_load_lds_dwordx4 v162, s[4:5]
	s_add_u32 m0, s62, 0x1000
	s_add_u32 s4, s56, 0x72000
	s_addc_u32 s5, s57, 0
	global_load_lds_dwordx4 v162, s[4:5]
	s_add_u32 m0, s62, 0x2000
	s_add_u32 s4, s56, 0xe4000
	s_addc_u32 s5, s57, 0
	global_load_lds_dwordx4 v162, s[4:5]
	s_add_u32 m0, s62, 0x3000
	s_add_u32 s4, s56, 0x156000
	s_addc_u32 s5, s57, 0
	global_load_lds_dwordx4 v162, s[4:5]
	s_add_u32 m0, s62, 0x4000
	s_add_u32 s4, s56, 0x1c8000
	s_addc_u32 s5, s57, 0
	global_load_lds_dwordx4 v162, s[4:5]
	s_add_u32 m0, s62, 0x5000
	s_add_u32 s4, s56, 0x23a000
	s_addc_u32 s5, s57, 0
	global_load_lds_dwordx4 v162, s[4:5]
	s_add_u32 m0, s62, 0x6000
	s_add_u32 s4, s56, 0x2ac000
	s_addc_u32 s5, s57, 0
	global_load_lds_dwordx4 v162, s[4:5]
	s_add_u32 m0, s62, 0x7000
	s_add_u32 s4, s56, 0x31e000
	s_addc_u32 s5, s57, 0
	global_load_lds_dwordx4 v162, s[4:5]
.Lg2_up_nd16_0:
	v_mfma_f32_16x16x32_bf16 v[96:99], v[188:191], v[164:167], v[96:99]
	v_mfma_f32_16x16x32_bf16 v[100:103], v[196:199], v[164:167], v[100:103]
	v_mfma_f32_16x16x32_bf16 v[104:107], v[188:191], v[168:171], v[104:107]
	v_mfma_f32_16x16x32_bf16 v[108:111], v[196:199], v[168:171], v[108:111]
	v_mfma_f32_16x16x32_bf16 v[112:115], v[188:191], v[172:175], v[112:115]
	v_mfma_f32_16x16x32_bf16 v[116:119], v[196:199], v[172:175], v[116:119]
	v_mfma_f32_16x16x32_bf16 v[120:123], v[188:191], v[176:179], v[120:123]
	v_mfma_f32_16x16x32_bf16 v[124:127], v[196:199], v[176:179], v[124:127]
	s_cmp_ge_u32 s63, 2
	s_cbranch_scc1 .Lg2_up_nb16_1
	s_add_u32 s58, s58, 0x800
	s_addc_u32 s59, s59, 0
	global_load_dwordx4 v[184:187], v160, s[58:59] offset:0
	global_load_dwordx4 v[188:191], v160, s[58:59] offset:1024
	global_load_dwordx4 v[192:195], v161, s[58:59] offset:0
	global_load_dwordx4 v[196:199], v161, s[58:59] offset:1024
.Lg2_up_nb16_1:
	ds_read_b128 v[164:167], v158 offset:8192
	ds_read_b128 v[168:171], v158 offset:10240
	ds_read_b128 v[172:175], v158 offset:12288
	ds_read_b128 v[176:179], v158 offset:14336
	s_waitcnt lgkmcnt(4)
	v_mfma_f32_16x16x32_bf16 v[0:3], v[200:203], v[136:139], v[0:3]
	v_mfma_f32_16x16x32_bf16 v[4:7], v[208:211], v[136:139], v[4:7]
	v_mfma_f32_16x16x32_bf16 v[8:11], v[200:203], v[140:143], v[8:11]
	v_mfma_f32_16x16x32_bf16 v[12:15], v[208:211], v[140:143], v[12:15]
	v_mfma_f32_16x16x32_bf16 v[16:19], v[200:203], v[144:147], v[16:19]
	v_mfma_f32_16x16x32_bf16 v[20:23], v[208:211], v[144:147], v[20:23]
	v_mfma_f32_16x16x32_bf16 v[24:27], v[200:203], v[148:151], v[24:27]
	v_mfma_f32_16x16x32_bf16 v[28:31], v[208:211], v[148:151], v[28:31]
	ds_read_b128 v[136:139], v158 offset:16384
	ds_read_b128 v[140:143], v158 offset:18432
	ds_read_b128 v[144:147], v158 offset:20480
	ds_read_b128 v[148:151], v158 offset:22528
	s_waitcnt lgkmcnt(4)
	v_mfma_f32_16x16x32_bf16 v[32:35], v[200:203], v[164:167], v[32:35]
	v_mfma_f32_16x16x32_bf16 v[36:39], v[208:211], v[164:167], v[36:39]
	v_mfma_f32_16x16x32_bf16 v[40:43], v[200:203], v[168:171], v[40:43]
	v_mfma_f32_16x16x32_bf16 v[44:47], v[208:211], v[168:171], v[44:47]
	v_mfma_f32_16x16x32_bf16 v[48:51], v[200:203], v[172:175], v[48:51]
	v_mfma_f32_16x16x32_bf16 v[52:55], v[208:211], v[172:175], v[52:55]
	v_mfma_f32_16x16x32_bf16 v[56:59], v[200:203], v[176:179], v[56:59]
	v_mfma_f32_16x16x32_bf16 v[60:63], v[208:211], v[176:179], v[60:63]
	ds_read_b128 v[164:167], v158 offset:24576
	ds_read_b128 v[168:171], v158 offset:26624
	ds_read_b128 v[172:175], v158 offset:28672
	ds_read_b128 v[176:179], v158 offset:30720
	s_waitcnt lgkmcnt(4)
	v_mfma_f32_16x16x32_bf16 v[64:67], v[200:203], v[136:139], v[64:67]
	v_mfma_f32_16x16x32_bf16 v[68:71], v[208:211], v[136:139], v[68:71]
	v_mfma_f32_16x16x32_bf16 v[72:75], v[200:203], v[140:143], v[72:75]
	v_mfma_f32_16x16x32_bf16 v[76:79], v[208:211], v[140:143], v[76:79]
	v_mfma_f32_16x16x32_bf16 v[80:83], v[200:203], v[144:147], v[80:83]
	v_mfma_f32_16x16x32_bf16 v[84:87], v[208:211], v[144:147], v[84:87]
	v_mfma_f32_16x16x32_bf16 v[88:91], v[200:203], v[148:151], v[88:91]
	v_mfma_f32_16x16x32_bf16 v[92:95], v[208:211], v[148:151], v[92:95]
	ds_read_b128 v[136:139], v159 offset:0
	ds_read_b128 v[140:143], v159 offset:2048
	ds_read_b128 v[144:147], v159 offset:4096
	ds_read_b128 v[148:151], v159 offset:6144
	s_waitcnt lgkmcnt(4)
	v_mfma_f32_16x16x32_bf16 v[96:99], v[200:203], v[164:167], v[96:99]
	v_mfma_f32_16x16x32_bf16 v[100:103], v[208:211], v[164:167], v[100:103]
	v_mfma_f32_16x16x32_bf16 v[104:107], v[200:203], v[168:171], v[104:107]
	v_mfma_f32_16x16x32_bf16 v[108:111], v[208:211], v[168:171], v[108:111]
	v_mfma_f32_16x16x32_bf16 v[112:115], v[200:203], v[172:175], v[112:115]
	v_mfma_f32_16x16x32_bf16 v[116:119], v[208:211], v[172:175], v[116:119]
	v_mfma_f32_16x16x32_bf16 v[120:123], v[200:203], v[176:179], v[120:123]
	v_mfma_f32_16x16x32_bf16 v[124:127], v[208:211], v[176:179], v[124:127]
	ds_read_b128 v[164:167], v159 offset:8192
	ds_read_b128 v[168:171], v159 offset:10240
	ds_read_b128 v[172:175], v159 offset:12288
	ds_read_b128 v[176:179], v159 offset:14336
	s_waitcnt lgkmcnt(4)
	v_mfma_f32_16x16x32_bf16 v[0:3], v[204:207], v[136:139], v[0:3]
	v_mfma_f32_16x16x32_bf16 v[4:7], v[240:243], v[136:139], v[4:7]
	v_mfma_f32_16x16x32_bf16 v[8:11], v[204:207], v[140:143], v[8:11]
	v_mfma_f32_16x16x32_bf16 v[12:15], v[240:243], v[140:143], v[12:15]
	v_mfma_f32_16x16x32_bf16 v[16:19], v[204:207], v[144:147], v[16:19]
	v_mfma_f32_16x16x32_bf16 v[20:23], v[240:243], v[144:147], v[20:23]
	v_mfma_f32_16x16x32_bf16 v[24:27], v[204:207], v[148:151], v[24:27]
	v_mfma_f32_16x16x32_bf16 v[28:31], v[240:243], v[148:151], v[28:31]
	ds_read_b128 v[136:139], v159 offset:16384
	ds_read_b128 v[140:143], v159 offset:18432
	ds_read_b128 v[144:147], v159 offset:20480
	ds_read_b128 v[148:151], v159 offset:22528
	s_waitcnt lgkmcnt(4)
	v_mfma_f32_16x16x32_bf16 v[32:35], v[204:207], v[164:167], v[32:35]
	v_mfma_f32_16x16x32_bf16 v[36:39], v[240:243], v[164:167], v[36:39]
	v_mfma_f32_16x16x32_bf16 v[40:43], v[204:207], v[168:171], v[40:43]
	v_mfma_f32_16x16x32_bf16 v[44:47], v[240:243], v[168:171], v[44:47]
	v_mfma_f32_16x16x32_bf16 v[48:51], v[204:207], v[172:175], v[48:51]
	v_mfma_f32_16x16x32_bf16 v[52:55], v[240:243], v[172:175], v[52:55]
	v_mfma_f32_16x16x32_bf16 v[56:59], v[204:207], v[176:179], v[56:59]
	v_mfma_f32_16x16x32_bf16 v[60:63], v[240:243], v[176:179], v[60:63]
	ds_read_b128 v[164:167], v159 offset:24576
	ds_read_b128 v[168:171], v159 offset:26624
	ds_read_b128 v[172:175], v159 offset:28672
	ds_read_b128 v[176:179], v159 offset:30720
	s_waitcnt lgkmcnt(4)
	v_mfma_f32_16x16x32_bf16 v[64:67], v[204:207], v[136:139], v[64:67]
	v_mfma_f32_16x16x32_bf16 v[68:71], v[240:243], v[136:139], v[68:71]
	v_mfma_f32_16x16x32_bf16 v[72:75], v[204:207], v[140:143], v[72:75]
	v_mfma_f32_16x16x32_bf16 v[76:79], v[240:243], v[140:143], v[76:79]
	v_mfma_f32_16x16x32_bf16 v[80:83], v[204:207], v[144:147], v[80:83]
	v_mfma_f32_16x16x32_bf16 v[84:87], v[240:243], v[144:147], v[84:87]
	v_mfma_f32_16x16x32_bf16 v[88:91], v[204:207], v[148:151], v[88:91]
	v_mfma_f32_16x16x32_bf16 v[92:95], v[240:243], v[148:151], v[92:95]
	s_waitcnt vmcnt(0) lgkmcnt(0)
	s_barrier
	s_cmp_ge_u32 s63, 2
	s_cbranch_scc1 .Lg2_up_nd16_1
	ds_read_b128 v[136:139], v156 offset:0
	ds_read_b128 v[140:143], v156 offset:2048
	ds_read_b128 v[144:147], v156 offset:4096
	ds_read_b128 v[148:151], v156 offset:6144
	s_add_u32 s56, s56, 0x80
	s_addc_u32 s57, s57, 0
	s_add_u32 m0, s62, 0x8800
	s_add_u32 s4, s56, 0x0
	s_addc_u32 s5, s57, 0
	global_load_lds_dwordx4 v162, s[4:5]
	s_add_u32 m0, s62, 0x9800
	s_add_u32 s4, s56, 0x72000
	s_addc_u32 s5, s57, 0
	global_load_lds_dwordx4 v162, s[4:5]
	s_add_u32 m0, s62, 0xa800
	s_add_u32 s4, s56, 0xe4000
	s_addc_u32 s5, s57, 0
	global_load_lds_dwordx4 v162, s[4:5]
	s_add_u32 m0, s62, 0xb800
	s_add_u32 s4, s56, 0x156000
	s_addc_u32 s5, s57, 0
	global_load_lds_dwordx4 v162, s[4:5]
	s_add_u32 m0, s62, 0xc800
	s_add_u32 s4, s56, 0x1c8000
	s_addc_u32 s5, s57, 0
	global_load_lds_dwordx4 v162, s[4:5]
	s_add_u32 m0, s62, 0xd800
	s_add_u32 s4, s56, 0x23a000
	s_addc_u32 s5, s57, 0
	global_load_lds_dwordx4 v162, s[4:5]
	s_add_u32 m0, s62, 0xe800
	s_add_u32 s4, s56, 0x2ac000
	s_addc_u32 s5, s57, 0
	global_load_lds_dwordx4 v162, s[4:5]
	s_add_u32 m0, s62, 0xf800
	s_add_u32 s4, s56, 0x31e000
	s_addc_u32 s5, s57, 0
	global_load_lds_dwordx4 v162, s[4:5]
